# P1 GEMM: peeled first K-iteration per unit (first MFMA per accumulator takes C=0 so the zeroing moves go away; first two waits relaxed to vmcnt(8+n_stores) so epilogue stores drain under MFMAs)
# speedup vs baseline: 1.0011x; 1.0011x over previous
.LBB0_95:
	s_mov_b32 s2, s0
	v_writelane_b32 v254, s2, 36
	s_lshl_b32 s0, s0, 3
	v_readlane_b32 s4, v252, 6
	v_writelane_b32 v254, s3, 37
	s_or_b32 s2, s0, 1
	v_readlane_b32 s5, v252, 7
	s_cmp_le_i32 s4, s2
	v_writelane_b32 v254, s0, 38
	s_cselect_b64 s[0:1], -1, 0
	s_cmp_lt_i32 s2, s5
	s_cselect_b64 s[4:5], -1, 0
	s_and_b64 s[10:11], s[0:1], s[4:5]
	s_andn2_b64 vcc, exec, s[10:11]
	s_cbranch_vccnz .LBB0_184
	s_mov_b32 s98, 0
	v_readlane_b32 s0, v254, 20
	v_readlane_b32 s2, v252, 2
	v_readlane_b32 s16, v252, 15
	v_mov_b32_e32 v0, s0
	s_waitcnt vmcnt(19)
	ds_read_b64 v[2:3], v0
	v_mov_b32_e32 v0, v1
	v_readlane_b32 s0, v252, 16
	v_mbcnt_lo_u32_b32 v0, -1, v0
	v_readlane_b32 s1, v252, 17
	s_waitcnt lgkmcnt(0)
	v_readfirstlane_b32 s37, v3
	v_readfirstlane_b32 s36, v2
	v_mbcnt_hi_u32_b32 v2, -1, v0
	s_andn2_b64 vcc, exec, s[0:1]
	s_cbranch_vccnz .LBB0_122
	v_readlane_b32 s0, v254, 36
	v_readlane_b32 s1, v254, 37
	s_mul_i32 s18, s0, 0x2680000
	s_add_u32 s4, s36, 0x28d00000
	s_addc_u32 s5, s37, 0
	s_lshl_b64 s[0:1], s[18:19], 1
	s_add_u32 s0, s36, s0
	s_addc_u32 s1, s37, s1
	s_add_u32 s6, s0, 0x100000
	s_addc_u32 s7, s1, 0
	s_lshl_b32 s8, s16, 10
	v_lshlrev_b32_e32 v3, 4, v2
	s_waitcnt vmcnt(9)
	v_add_u32_e32 v4, s8, v3
	v_add_u32_e32 v5, 0x2000, v4
	v_ashrrev_i32_e32 v0, 31, v5
	v_lshrrev_b32_e32 v0, 22, v0
	v_add_u32_e32 v0, v5, v0
	v_ashrrev_i32_e32 v0, 10, v0
	v_mul_i32_i24_e32 v6, 0x400, v0
	v_sub_u32_e32 v5, v5, v6
	v_lshrrev_b32_e32 v6, 4, v5
	v_bitop3_b32 v5, v6, v5, 32 bitop3:0x6c
	v_ashrrev_i32_e32 v6, 31, v5
	v_lshrrev_b32_e32 v6, 26, v6
	v_add_u32_e32 v6, v5, v6
	v_lshlrev_b32_e32 v7, 3, v0
	v_ashrrev_i32_e32 v12, 6, v6
	v_and_b32_e32 v7, -16, v7
	v_and_b32_e32 v6, 0xffc0, v6
	v_add_u32_e32 v7, v12, v7
	v_sub_u32_e32 v5, v5, v6
	s_waitcnt vmcnt(8)
	v_and_b32_e32 v8, 3, v12
	s_mov_b32 s0, 0xfffe0
	v_lshrrev_b32_e32 v9, 2, v7
	v_lshlrev_b32_e32 v10, 1, v7
	v_lshrrev_b16_e32 v6, 7, v5
	v_and_or_b32 v8, v7, s0, v8
	v_and_b32_e32 v9, 4, v9
	v_and_b32_e32 v10, 24, v10
	v_and_b32_e32 v6, 1, v6
	v_or3_b32 v8, v8, v9, v10
	v_add_u16_e32 v5, v5, v6
	v_mov_b32_e32 v10, 1
	v_lshlrev_b32_e32 v9, 5, v0
	v_ashrrev_i16_sdwa v5, v10, sext(v5) dst_sel:DWORD dst_unused:UNUSED_PAD src0_sel:DWORD src1_sel:BYTE_0
	v_and_b32_e32 v9, 32, v9
	v_bfe_i32 v13, v5, 0, 16
	v_add_lshl_u32 v5, v9, v13, 1
	v_lshl_add_u32 v130, v8, 12, v5
	v_lshl_add_u32 v132, v7, 12, v5
	v_ashrrev_i32_e32 v5, 31, v4
	v_lshrrev_b32_e32 v5, 22, v5
	v_add_u32_e32 v5, v4, v5
	s_waitcnt vmcnt(0)
	v_ashrrev_i32_e32 v14, 10, v5
	v_mul_i32_i24_e32 v5, 0x400, v14
	v_sub_u32_e32 v4, v4, v5
	v_lshrrev_b32_e32 v5, 4, v4
	v_bitop3_b32 v4, v5, v4, 32 bitop3:0x6c
	v_ashrrev_i32_e32 v5, 31, v4
	v_lshrrev_b32_e32 v5, 26, v5
	v_add_u32_e32 v5, v4, v5
	v_lshlrev_b32_e32 v6, 3, v14
	v_ashrrev_i32_e32 v15, 6, v5
	v_and_b32_e32 v6, -16, v6
	v_add_u32_e32 v6, v15, v6
	v_and_b32_e32 v7, 3, v15
	v_lshrrev_b32_e32 v8, 2, v6
	v_lshlrev_b32_e32 v9, 1, v6
	v_and_b32_e32 v5, 0xc0, v5
	v_and_or_b32 v7, v6, s0, v7
	v_and_b32_e32 v8, 4, v8
	v_and_b32_e32 v9, 24, v9
	v_sub_u32_e32 v4, v4, v5
	s_ashr_i32 s18, s16, 2
	v_or3_b32 v7, v7, v8, v9
	v_lshlrev_b32_e32 v8, 5, v14
	v_ashrrev_i16_sdwa v4, v10, sext(v4) dst_sel:DWORD dst_unused:UNUSED_PAD src0_sel:DWORD src1_sel:BYTE_0
	v_readlane_b32 s0, v254, 6
	v_and_b32_e32 v8, 32, v8
	v_bfe_i32 v16, v4, 0, 16
	v_readlane_b32 s1, v254, 7
	s_add_u32 s0, s6, s0
	v_add_lshl_u32 v4, v8, v16, 1
	s_addc_u32 s1, s7, s1
	s_add_i32 s9, s8, 0
	v_lshl_add_u32 v134, v7, 12, v4
	s_add_i32 m0, s9, 0x10000
	v_lshl_add_u32 v136, v6, 12, v4
	global_load_lds_dwordx4 v134, s[0:1]
	s_add_i32 m0, s9, 0x12000
	s_add_u32 s12, s0, 0x80000
	global_load_lds_dwordx4 v130, s[0:1]
	s_addc_u32 s13, s1, 0
	s_add_i32 m0, s9, 0x14000
	v_mov_b32_e32 v135, v1
	global_load_lds_dwordx4 v134, s[12:13]
	s_add_i32 m0, s9, 0x16000
	v_mov_b32_e32 v131, v1
	global_load_lds_dwordx4 v130, s[12:13]
	v_readlane_b32 s12, v254, 2
	v_readlane_b32 s13, v254, 3
	s_add_u32 s48, s4, s12
	s_addc_u32 s49, s5, s13
	s_add_i32 s28, s9, 0x2000
	s_mov_b32 m0, s9
	s_add_u32 s12, s48, 0x80000
	global_load_lds_dwordx4 v136, s[48:49]
	s_mov_b32 m0, s28
	s_addc_u32 s13, s49, 0
	s_add_i32 s29, s9, 0x4000
	global_load_lds_dwordx4 v132, s[48:49]
	s_mov_b32 m0, s29
	s_add_i32 s35, s9, 0x6000
	global_load_lds_dwordx4 v136, s[12:13]
	s_mov_b32 m0, s35
	v_mov_b32_e32 v137, v1
	global_load_lds_dwordx4 v132, s[12:13]
	v_mov_b32_e32 v133, v1
	s_cmp_eq_u32 s18, 1
	v_lshl_add_u64 v[10:11], s[0:1], 0, v[134:135]
	v_lshl_add_u64 v[8:9], s[0:1], 0, v[130:131]
	v_lshl_add_u64 v[4:5], s[48:49], 0, v[136:137]
	s_cselect_b64 s[12:13], -1, 0
	s_cmp_lg_u32 s18, 1
	v_lshl_add_u64 v[6:7], s[48:49], 0, v[132:133]
	s_cbranch_scc1 .LBB0_99
	s_barrier

.LBB0_104:
	s_add_i32 s30, s38, 0x44
	s_add_i32 s31, s38, 0xffffffbc
	s_cmp_lt_u32 s31, 8
	s_cselect_b32 s31, s31, s38
	s_cmp_lt_i32 s38, 8
	s_cselect_b32 s38, s30, s31
	s_ashr_i32 s41, s40, 31
	s_lshl_b64 s[30:31], s[40:41], 20
	s_add_u32 s42, s4, s30
	s_addc_u32 s43, s5, s31
	s_and_b64 s[30:31], s[36:37], exec
	s_cselect_b32 s41, s43, s49
	s_cselect_b32 s47, s42, s48
	s_ashr_i32 s39, s38, 31
	s_lshl_b64 s[30:31], s[38:39], 20
	s_add_u32 s44, s6, s30
	s_addc_u32 s45, s7, s31
	s_and_b64 s[30:31], s[36:37], exec
	s_cselect_b32 s39, s45, s1
	s_cselect_b32 s55, s44, s0
	s_add_u32 s60, s0, 0x100
	s_addc_u32 s61, s1, 0
	s_add_u32 s0, s48, 0x80080
	s_addc_u32 s1, s49, 0
	s_mov_b32 s62, -2
	s_add_u32 s30, s0, 0xfff80080
	s_addc_u32 s31, s1, -1
	s_add_i32 s63, 0, 0x10000
	s_cmp_eq_u32 s62, 28
	s_cselect_b32 s51, s41, s31
	s_cselect_b32 s50, s47, s30
	v_add_u32_e32 v150, s63, v153
	s_cselect_b32 s49, s39, s61
	s_cselect_b32 s48, s55, s60
	s_add_i32 s64, 0, 0x14000
	ds_read_b128 v[146:149], v150
	ds_read_b128 v[156:159], v150 offset:1024
	ds_read_b128 v[160:163], v150 offset:2048
	ds_read_b128 v[174:177], v150 offset:3072
	v_add_u32_e32 v150, s64, v153
	ds_read_b128 v[178:181], v150
	ds_read_b128 v[182:185], v150 offset:1024
	ds_read_b128 v[186:189], v150 offset:2048
	ds_read_b128 v[190:193], v150 offset:3072
	v_lshl_add_u64 v[150:151], s[0:1], 0, v[144:145]
	s_add_i32 m0, s9, 0xc000
	ds_read_b128 v[194:197], v155
	ds_read_b128 v[198:201], v155 offset:1024
	ds_read_b128 v[202:205], v155 offset:2048
	ds_read_b128 v[206:209], v155 offset:3072
	ds_read_b128 v[218:221], v155 offset:4096
	ds_read_b128 v[222:225], v155 offset:5120
	ds_read_b128 v[226:229], v155 offset:6144
	ds_read_b128 v[230:233], v155 offset:7168
	global_load_lds_dwordx4 v[150:151], off
	v_lshl_add_u64 v[150:151], s[0:1], 0, v[142:143]
	s_add_i32 m0, s9, 0xe000
	s_nop 0
	global_load_lds_dwordx4 v[150:151], off
	s_cmp_eq_u32 s98, 16
	s_cbranch_scc1 .Lp1pk_w1_16
	s_cmp_eq_u32 s98, 8
	s_cbranch_scc1 .Lp1pk_w1_8
	s_waitcnt vmcnt(8)
	s_branch .Lp1pk_w1_done
.Lp1pk_w1_16:
	s_waitcnt vmcnt(24)
	s_branch .Lp1pk_w1_done
.Lp1pk_w1_8:
	s_waitcnt vmcnt(16)
.Lp1pk_w1_done:
	s_waitcnt lgkmcnt(0)
	s_barrier
	s_setprio 1
	s_waitcnt lgkmcnt(0)
	v_mfma_f32_16x16x32_bf16 v[70:73], v[146:149], v[194:197], 0
	v_mfma_f32_16x16x32_bf16 v[66:69], v[160:163], v[194:197], 0
	v_mfma_f32_16x16x32_bf16 v[62:65], v[146:149], v[202:205], 0
	v_mfma_f32_16x16x32_bf16 v[58:61], v[160:163], v[202:205], 0
	v_mfma_f32_16x16x32_bf16 v[50:53], v[146:149], v[218:221], 0
	v_mfma_f32_16x16x32_bf16 v[46:49], v[160:163], v[218:221], 0
	v_mfma_f32_16x16x32_bf16 v[42:45], v[146:149], v[226:229], 0
	v_mfma_f32_16x16x32_bf16 v[38:41], v[160:163], v[226:229], 0
	v_mfma_f32_16x16x32_bf16 v[70:73], v[156:159], v[198:201], v[70:73]
	v_mfma_f32_16x16x32_bf16 v[66:69], v[174:177], v[198:201], v[66:69]
	v_mfma_f32_16x16x32_bf16 v[62:65], v[156:159], v[206:209], v[62:65]
	v_mfma_f32_16x16x32_bf16 v[58:61], v[174:177], v[206:209], v[58:61]
	v_mfma_f32_16x16x32_bf16 v[50:53], v[156:159], v[222:225], v[50:53]
	v_mfma_f32_16x16x32_bf16 v[46:49], v[174:177], v[222:225], v[46:49]
	v_mfma_f32_16x16x32_bf16 v[42:45], v[156:159], v[230:233], v[42:45]
	v_mfma_f32_16x16x32_bf16 v[38:41], v[174:177], v[230:233], v[38:41]
	s_setprio 0
	s_setprio 1
	v_mfma_f32_16x16x32_bf16 v[126:129], v[178:181], v[194:197], 0
	v_mfma_f32_16x16x32_bf16 v[122:125], v[186:189], v[194:197], 0
	v_mfma_f32_16x16x32_bf16 v[118:121], v[178:181], v[202:205], 0
	v_mfma_f32_16x16x32_bf16 v[114:117], v[186:189], v[202:205], 0
	v_mfma_f32_16x16x32_bf16 v[110:113], v[178:181], v[218:221], 0
	v_mfma_f32_16x16x32_bf16 v[106:109], v[186:189], v[218:221], 0
	v_mfma_f32_16x16x32_bf16 v[102:105], v[178:181], v[226:229], 0
	v_mfma_f32_16x16x32_bf16 v[98:101], v[186:189], v[226:229], 0
	v_mfma_f32_16x16x32_bf16 v[126:129], v[182:185], v[198:201], v[126:129]
	v_mfma_f32_16x16x32_bf16 v[122:125], v[190:193], v[198:201], v[122:125]
	v_mfma_f32_16x16x32_bf16 v[118:121], v[182:185], v[206:209], v[118:121]
	v_mfma_f32_16x16x32_bf16 v[114:117], v[190:193], v[206:209], v[114:117]
	v_mfma_f32_16x16x32_bf16 v[110:113], v[182:185], v[222:225], v[110:113]
	v_mfma_f32_16x16x32_bf16 v[106:109], v[190:193], v[222:225], v[106:109]
	v_mfma_f32_16x16x32_bf16 v[102:105], v[182:185], v[230:233], v[102:105]
	v_mfma_f32_16x16x32_bf16 v[98:101], v[190:193], v[230:233], v[98:101]
	s_setprio 0
	s_barrier
	s_add_i32 s30, s63, s8
	v_lshl_add_u64 v[150:151], s[48:49], 0, v[134:135]
	s_mov_b32 m0, s30
	ds_read_b128 v[194:197], v155 offset:16384
	ds_read_b128 v[198:201], v155 offset:17408
	ds_read_b128 v[202:205], v155 offset:18432
	ds_read_b128 v[206:209], v155 offset:19456
	ds_read_b128 v[218:221], v155 offset:20480
	ds_read_b128 v[222:225], v155 offset:21504
	ds_read_b128 v[226:229], v155 offset:22528
	ds_read_b128 v[230:233], v155 offset:23552
	global_load_lds_dwordx4 v[150:151], off
	s_add_i32 m0, s30, 0x2000
	s_add_u32 s30, s48, 0x80000
	v_lshl_add_u64 v[164:165], s[48:49], 0, v[130:131]
	s_addc_u32 s31, s49, 0
	s_add_i32 s63, s64, s8
	global_load_lds_dwordx4 v[164:165], off
	v_lshl_add_u64 v[166:167], s[30:31], 0, v[134:135]
	s_mov_b32 m0, s63
	v_lshl_add_u64 v[170:171], s[50:51], 0, v[132:133]
	global_load_lds_dwordx4 v[166:167], off
	v_lshl_add_u64 v[166:167], s[30:31], 0, v[130:131]
	s_add_i32 m0, s63, 0x2000
	s_nop 0
	global_load_lds_dwordx4 v[166:167], off
	v_lshl_add_u64 v[166:167], s[50:51], 0, v[136:137]
	s_mov_b32 m0, s9
	s_nop 0
	global_load_lds_dwordx4 v[166:167], off
	s_mov_b32 m0, s28
	s_nop 0
	global_load_lds_dwordx4 v[170:171], off
	s_cmp_eq_u32 s98, 16
	s_cbranch_scc1 .Lp1pk_w2_16
	s_cmp_eq_u32 s98, 8
	s_cbranch_scc1 .Lp1pk_w2_8
	s_waitcnt vmcnt(8)
	s_branch .Lp1pk_w2_done

.Lp1pk_w2_done:
	s_waitcnt lgkmcnt(0)
	s_barrier
	s_setprio 1
	s_waitcnt lgkmcnt(0)
	v_mfma_f32_16x16x32_bf16 v[30:33], v[146:149], v[194:197], 0
	v_mfma_f32_16x16x32_bf16 v[26:29], v[160:163], v[194:197], 0
	v_mfma_f32_16x16x32_bf16 v[22:25], v[146:149], v[202:205], 0
	v_mfma_f32_16x16x32_bf16 v[18:21], v[160:163], v[202:205], 0
	v_mfma_f32_16x16x32_bf16 v[14:17], v[146:149], v[218:221], 0
	v_mfma_f32_16x16x32_bf16 v[10:13], v[160:163], v[218:221], 0
	v_mfma_f32_16x16x32_bf16 v[6:9], v[146:149], v[226:229], 0
	v_mfma_f32_16x16x32_bf16 v[2:5], v[160:163], v[226:229], 0
	v_mfma_f32_16x16x32_bf16 v[30:33], v[156:159], v[198:201], v[30:33]
	v_mfma_f32_16x16x32_bf16 v[26:29], v[174:177], v[198:201], v[26:29]
	v_mfma_f32_16x16x32_bf16 v[22:25], v[156:159], v[206:209], v[22:25]
	v_mfma_f32_16x16x32_bf16 v[18:21], v[174:177], v[206:209], v[18:21]
	v_mfma_f32_16x16x32_bf16 v[14:17], v[156:159], v[222:225], v[14:17]
	v_mfma_f32_16x16x32_bf16 v[10:13], v[174:177], v[222:225], v[10:13]
	v_mfma_f32_16x16x32_bf16 v[6:9], v[156:159], v[230:233], v[6:9]
	v_mfma_f32_16x16x32_bf16 v[2:5], v[174:177], v[230:233], v[2:5]
	s_setprio 0
	s_setprio 1
	v_mfma_f32_16x16x32_bf16 v[94:97], v[178:181], v[194:197], 0
	v_mfma_f32_16x16x32_bf16 v[90:93], v[186:189], v[194:197], 0
	v_mfma_f32_16x16x32_bf16 v[86:89], v[178:181], v[202:205], 0
	v_mfma_f32_16x16x32_bf16 v[82:85], v[186:189], v[202:205], 0
	v_mfma_f32_16x16x32_bf16 v[78:81], v[178:181], v[218:221], 0
	v_mfma_f32_16x16x32_bf16 v[74:77], v[186:189], v[218:221], 0
	v_mfma_f32_16x16x32_bf16 v[54:57], v[178:181], v[226:229], 0
	v_mfma_f32_16x16x32_bf16 v[34:37], v[186:189], v[226:229], 0
	v_mfma_f32_16x16x32_bf16 v[94:97], v[182:185], v[198:201], v[94:97]
	v_mfma_f32_16x16x32_bf16 v[90:93], v[190:193], v[198:201], v[90:93]
	v_mfma_f32_16x16x32_bf16 v[86:89], v[182:185], v[206:209], v[86:89]
	v_mfma_f32_16x16x32_bf16 v[82:85], v[190:193], v[206:209], v[82:85]
	v_mfma_f32_16x16x32_bf16 v[78:81], v[182:185], v[222:225], v[78:81]
	v_mfma_f32_16x16x32_bf16 v[74:77], v[190:193], v[222:225], v[74:77]
	v_mfma_f32_16x16x32_bf16 v[54:57], v[182:185], v[230:233], v[54:57]
	v_mfma_f32_16x16x32_bf16 v[34:37], v[190:193], v[230:233], v[34:37]
	s_setprio 0
	s_barrier
	s_add_i32 s63, 0, 0x18000
	v_add_u32_e32 v172, s63, v153
	s_add_i32 s64, 0, 0x1c000
	ds_read_b128 v[146:149], v172
	ds_read_b128 v[156:159], v172 offset:1024
	ds_read_b128 v[160:163], v172 offset:2048
	ds_read_b128 v[174:177], v172 offset:3072
	v_add_u32_e32 v172, s64, v153
	ds_read_b128 v[178:181], v172
	ds_read_b128 v[182:185], v172 offset:1024
	ds_read_b128 v[186:189], v172 offset:2048
	ds_read_b128 v[190:193], v172 offset:3072
	s_add_u32 s30, s50, 0x80000
	s_addc_u32 s31, s51, 0
	s_mov_b32 m0, s29
	v_lshl_add_u64 v[172:173], s[30:31], 0, v[136:137]
	ds_read_b128 v[194:197], v155 offset:32768
	ds_read_b128 v[198:201], v155 offset:33792
	ds_read_b128 v[202:205], v155 offset:34816
	ds_read_b128 v[206:209], v155 offset:35840
	ds_read_b128 v[218:221], v155 offset:36864
	ds_read_b128 v[222:225], v155 offset:37888
	ds_read_b128 v[226:229], v155 offset:38912
	ds_read_b128 v[230:233], v155 offset:39936
	global_load_lds_dwordx4 v[172:173], off
	v_lshl_add_u64 v[172:173], s[30:31], 0, v[132:133]
	s_mov_b32 m0, s35
	s_nop 0
	global_load_lds_dwordx4 v[172:173], off
	s_waitcnt vmcnt(8)
	s_waitcnt lgkmcnt(0)
	s_barrier
	s_setprio 1
	s_waitcnt lgkmcnt(0)
	v_mfma_f32_16x16x32_bf16 v[70:73], v[146:149], v[194:197], v[70:73]
	v_mfma_f32_16x16x32_bf16 v[66:69], v[160:163], v[194:197], v[66:69]
	v_mfma_f32_16x16x32_bf16 v[62:65], v[146:149], v[202:205], v[62:65]
	v_mfma_f32_16x16x32_bf16 v[58:61], v[160:163], v[202:205], v[58:61]
	v_mfma_f32_16x16x32_bf16 v[50:53], v[146:149], v[218:221], v[50:53]
	v_mfma_f32_16x16x32_bf16 v[46:49], v[160:163], v[218:221], v[46:49]
	v_mfma_f32_16x16x32_bf16 v[42:45], v[146:149], v[226:229], v[42:45]
	v_mfma_f32_16x16x32_bf16 v[38:41], v[160:163], v[226:229], v[38:41]
	v_mfma_f32_16x16x32_bf16 v[70:73], v[156:159], v[198:201], v[70:73]
	v_mfma_f32_16x16x32_bf16 v[66:69], v[174:177], v[198:201], v[66:69]
	v_mfma_f32_16x16x32_bf16 v[62:65], v[156:159], v[206:209], v[62:65]
	v_mfma_f32_16x16x32_bf16 v[58:61], v[174:177], v[206:209], v[58:61]
	v_mfma_f32_16x16x32_bf16 v[50:53], v[156:159], v[222:225], v[50:53]
	v_mfma_f32_16x16x32_bf16 v[46:49], v[174:177], v[222:225], v[46:49]
	v_mfma_f32_16x16x32_bf16 v[42:45], v[156:159], v[230:233], v[42:45]
	v_mfma_f32_16x16x32_bf16 v[38:41], v[174:177], v[230:233], v[38:41]
	s_setprio 0
	s_setprio 1
	v_mfma_f32_16x16x32_bf16 v[126:129], v[178:181], v[194:197], v[126:129]
	v_mfma_f32_16x16x32_bf16 v[122:125], v[186:189], v[194:197], v[122:125]
	v_mfma_f32_16x16x32_bf16 v[118:121], v[178:181], v[202:205], v[118:121]
	v_mfma_f32_16x16x32_bf16 v[114:117], v[186:189], v[202:205], v[114:117]
	v_mfma_f32_16x16x32_bf16 v[110:113], v[178:181], v[218:221], v[110:113]
	v_mfma_f32_16x16x32_bf16 v[106:109], v[186:189], v[218:221], v[106:109]
	v_mfma_f32_16x16x32_bf16 v[102:105], v[178:181], v[226:229], v[102:105]
	v_mfma_f32_16x16x32_bf16 v[98:101], v[186:189], v[226:229], v[98:101]
	v_mfma_f32_16x16x32_bf16 v[126:129], v[182:185], v[198:201], v[126:129]
	v_mfma_f32_16x16x32_bf16 v[122:125], v[190:193], v[198:201], v[122:125]
	v_mfma_f32_16x16x32_bf16 v[118:121], v[182:185], v[206:209], v[118:121]
	v_mfma_f32_16x16x32_bf16 v[114:117], v[190:193], v[206:209], v[114:117]
	v_mfma_f32_16x16x32_bf16 v[110:113], v[182:185], v[222:225], v[110:113]
	v_mfma_f32_16x16x32_bf16 v[106:109], v[190:193], v[222:225], v[106:109]
	v_mfma_f32_16x16x32_bf16 v[102:105], v[182:185], v[230:233], v[102:105]
	v_mfma_f32_16x16x32_bf16 v[98:101], v[190:193], v[230:233], v[98:101]
	s_setprio 0
	s_barrier
	s_add_i32 s30, s63, s8
	v_lshl_add_u64 v[150:151], v[150:151], 0, s[24:25]
	s_mov_b32 m0, s30
	ds_read_b128 v[194:197], v155 offset:49152
	ds_read_b128 v[198:201], v155 offset:50176
	ds_read_b128 v[202:205], v155 offset:51200
	ds_read_b128 v[206:209], v155 offset:52224
	ds_read_b128 v[218:221], v155 offset:53248
	ds_read_b128 v[222:225], v155 offset:54272
	ds_read_b128 v[226:229], v155 offset:55296
	ds_read_b128 v[230:233], v155 offset:56320
	global_load_lds_dwordx4 v[150:151], off
	s_add_i32 m0, s30, 0x2000
	s_add_u32 s30, s48, 0x80080
	v_lshl_add_u64 v[150:151], v[164:165], 0, s[24:25]
	s_addc_u32 s31, s49, 0
	s_add_i32 s48, s64, s8
	global_load_lds_dwordx4 v[150:151], off
	v_lshl_add_u64 v[150:151], s[30:31], 0, v[134:135]
	s_mov_b32 m0, s48
	s_nop 0
	global_load_lds_dwordx4 v[150:151], off
	v_lshl_add_u64 v[150:151], s[30:31], 0, v[130:131]
	s_add_i32 m0, s48, 0x2000
	s_nop 0
	global_load_lds_dwordx4 v[150:151], off
	v_lshl_add_u64 v[150:151], v[166:167], 0, s[24:25]
	s_mov_b32 m0, s52
	s_nop 0
	global_load_lds_dwordx4 v[150:151], off
	v_lshl_add_u64 v[150:151], v[170:171], 0, s[24:25]
	s_mov_b32 m0, s53
	s_nop 0
	global_load_lds_dwordx4 v[150:151], off
	s_waitcnt vmcnt(8)
	s_waitcnt lgkmcnt(0)
	s_barrier
	s_setprio 1
	s_waitcnt lgkmcnt(0)
	v_mfma_f32_16x16x32_bf16 v[30:33], v[146:149], v[194:197], v[30:33]
	v_mfma_f32_16x16x32_bf16 v[26:29], v[160:163], v[194:197], v[26:29]
	v_mfma_f32_16x16x32_bf16 v[22:25], v[146:149], v[202:205], v[22:25]
	v_mfma_f32_16x16x32_bf16 v[18:21], v[160:163], v[202:205], v[18:21]
	v_mfma_f32_16x16x32_bf16 v[14:17], v[146:149], v[218:221], v[14:17]
	v_mfma_f32_16x16x32_bf16 v[10:13], v[160:163], v[218:221], v[10:13]
	v_mfma_f32_16x16x32_bf16 v[6:9], v[146:149], v[226:229], v[6:9]
	v_mfma_f32_16x16x32_bf16 v[2:5], v[160:163], v[226:229], v[2:5]
	v_mfma_f32_16x16x32_bf16 v[30:33], v[156:159], v[198:201], v[30:33]
	v_mfma_f32_16x16x32_bf16 v[26:29], v[174:177], v[198:201], v[26:29]
	v_mfma_f32_16x16x32_bf16 v[22:25], v[156:159], v[206:209], v[22:25]
	v_mfma_f32_16x16x32_bf16 v[18:21], v[174:177], v[206:209], v[18:21]
	v_mfma_f32_16x16x32_bf16 v[14:17], v[156:159], v[222:225], v[14:17]
	v_mfma_f32_16x16x32_bf16 v[10:13], v[174:177], v[222:225], v[10:13]
	v_mfma_f32_16x16x32_bf16 v[6:9], v[156:159], v[230:233], v[6:9]
	v_mfma_f32_16x16x32_bf16 v[2:5], v[174:177], v[230:233], v[2:5]
	s_setprio 0
	s_setprio 1
	v_mfma_f32_16x16x32_bf16 v[94:97], v[178:181], v[194:197], v[94:97]
	v_mfma_f32_16x16x32_bf16 v[90:93], v[186:189], v[194:197], v[90:93]
	v_mfma_f32_16x16x32_bf16 v[86:89], v[178:181], v[202:205], v[86:89]
	v_mfma_f32_16x16x32_bf16 v[82:85], v[186:189], v[202:205], v[82:85]
	v_mfma_f32_16x16x32_bf16 v[78:81], v[178:181], v[218:221], v[78:81]
	v_mfma_f32_16x16x32_bf16 v[74:77], v[186:189], v[218:221], v[74:77]
	v_mfma_f32_16x16x32_bf16 v[54:57], v[178:181], v[226:229], v[54:57]
	v_mfma_f32_16x16x32_bf16 v[34:37], v[186:189], v[226:229], v[34:37]
	v_mfma_f32_16x16x32_bf16 v[94:97], v[182:185], v[198:201], v[94:97]
	v_mfma_f32_16x16x32_bf16 v[90:93], v[190:193], v[198:201], v[90:93]
	v_mfma_f32_16x16x32_bf16 v[86:89], v[182:185], v[206:209], v[86:89]
	v_mfma_f32_16x16x32_bf16 v[82:85], v[190:193], v[206:209], v[82:85]
	v_mfma_f32_16x16x32_bf16 v[78:81], v[182:185], v[222:225], v[78:81]
	v_mfma_f32_16x16x32_bf16 v[74:77], v[190:193], v[222:225], v[74:77]
	v_mfma_f32_16x16x32_bf16 v[54:57], v[182:185], v[230:233], v[54:57]
	v_mfma_f32_16x16x32_bf16 v[34:37], v[190:193], v[230:233], v[34:37]
	s_setprio 0
	s_barrier
	s_add_i32 s62, s62, 2
	s_add_u32 s60, s60, 0x100
	s_addc_u32 s61, s61, 0
	s_add_u32 s0, s0, 0x100
	s_addc_u32 s1, s1, 0
	s_cmp_gt_u32 s62, 29

.LBB0_108:
	s_mov_b32 s98, 0
	v_lshl_add_u32 v146, s46, 8, v152
	s_cmpk_lg_i32 s18, 0x4c
	s_mov_b64 s[0:1], -1
	v_readlane_b32 s61, v254, 34
	s_cbranch_scc0 .LBB0_115
	s_cmp_lt_i32 s18, 60
	s_cbranch_scc0 .LBB0_111
	s_mov_b32 s98, 16
	v_lshl_add_u32 v147, s18, 8, v154
	v_ashrrev_i32_e32 v148, 8, v147
	s_and_b32 s0, s18, -4
	v_ashrrev_i32_e32 v149, 31, v148
	s_cmp_eq_u32 s0, 36
	v_lshlrev_b64 v[148:149], 22, v[148:149]
	v_ashrrev_i32_e32 v147, 31, v146
	v_lshl_add_u64 v[150:151], s[14:15], 0, v[148:149]
	v_lshlrev_b64 v[148:149], 9, v[146:147]
	v_pk_mul_f32 v[156:157], v[72:73], s[26:27] op_sel_hi:[1,0]
	v_pk_mul_f32 v[158:159], v[70:71], s[26:27] op_sel_hi:[1,0]
	v_pk_mul_f32 v[160:161], v[68:69], s[26:27] op_sel_hi:[1,0]
	v_pk_mul_f32 v[162:163], v[66:67], s[26:27] op_sel_hi:[1,0]
	s_cselect_b64 vcc, -1, 0
	v_lshl_add_u64 v[148:149], v[150:151], 0, v[148:149]
	v_cndmask_b32_e32 v147, v73, v157, vcc
	v_cndmask_b32_e32 v157, v72, v156, vcc
	v_cndmask_b32_e32 v156, v71, v159, vcc
	v_cndmask_b32_e32 v158, v70, v158, vcc
	v_cndmask_b32_e32 v159, v69, v161, vcc
	v_cndmask_b32_e32 v160, v68, v160, vcc
	v_cndmask_b32_e32 v161, v67, v163, vcc
	v_cndmask_b32_e32 v162, v66, v162, vcc
	v_lshl_add_u64 v[148:149], v[148:149], 0, v[0:1]
	v_cvt_pk_bf16_f32 v156, v158, v156
	v_cvt_pk_bf16_f32 v157, v157, v147
	v_cvt_pk_bf16_f32 v158, v162, v161
	v_cvt_pk_bf16_f32 v159, v160, v159
	global_store_dwordx4 v[148:149], v[156:159], off
	v_pk_mul_f32 v[160:161], v[124:125], s[26:27] op_sel_hi:[1,0]
	v_pk_mul_f32 v[162:163], v[122:123], s[26:27] op_sel_hi:[1,0]
	v_pk_mul_f32 v[156:157], v[128:129], s[26:27] op_sel_hi:[1,0]
	v_pk_mul_f32 v[158:159], v[126:127], s[26:27] op_sel_hi:[1,0]
	v_cndmask_b32_e32 v147, v129, v157, vcc
	v_cndmask_b32_e32 v157, v128, v156, vcc
	v_cndmask_b32_e32 v156, v127, v159, vcc
	v_cndmask_b32_e32 v158, v126, v158, vcc
	v_cndmask_b32_e32 v159, v125, v161, vcc
	v_cndmask_b32_e32 v160, v124, v160, vcc
	v_cndmask_b32_e32 v161, v123, v163, vcc
	v_cndmask_b32_e32 v162, v122, v162, vcc
	v_cvt_pk_bf16_f32 v156, v158, v156
	v_cvt_pk_bf16_f32 v157, v157, v147
	v_cvt_pk_bf16_f32 v158, v162, v161
	v_cvt_pk_bf16_f32 v159, v160, v159
	global_store_dwordx4 v[148:149], v[156:159], off offset:256
	v_pk_mul_f32 v[162:163], v[60:61], s[26:27] op_sel_hi:[1,0]
	v_pk_mul_f32 v[164:165], v[58:59], s[26:27] op_sel_hi:[1,0]
	v_or_b32_e32 v156, 16, v146
	v_ashrrev_i32_e32 v157, 31, v156
	v_lshlrev_b64 v[156:157], 9, v[156:157]
	v_lshl_add_u64 v[156:157], v[150:151], 0, v[156:157]
	v_lshl_add_u64 v[160:161], v[156:157], 0, v[0:1]
	v_pk_mul_f32 v[156:157], v[64:65], s[26:27] op_sel_hi:[1,0]
	v_pk_mul_f32 v[158:159], v[62:63], s[26:27] op_sel_hi:[1,0]
	v_cndmask_b32_e32 v147, v65, v157, vcc
	v_cndmask_b32_e32 v157, v64, v156, vcc
	v_cndmask_b32_e32 v156, v63, v159, vcc
	v_cndmask_b32_e32 v158, v62, v158, vcc
	v_cndmask_b32_e32 v159, v61, v163, vcc
	v_cndmask_b32_e32 v162, v60, v162, vcc
	v_cndmask_b32_e32 v163, v59, v165, vcc
	v_cndmask_b32_e32 v164, v58, v164, vcc
	v_cvt_pk_bf16_f32 v156, v158, v156
	v_cvt_pk_bf16_f32 v157, v157, v147
	v_cvt_pk_bf16_f32 v158, v164, v163
	v_cvt_pk_bf16_f32 v159, v162, v159
	global_store_dwordx4 v[160:161], v[156:159], off
	v_pk_mul_f32 v[162:163], v[116:117], s[26:27] op_sel_hi:[1,0]
	v_pk_mul_f32 v[164:165], v[114:115], s[26:27] op_sel_hi:[1,0]
	v_pk_mul_f32 v[156:157], v[120:121], s[26:27] op_sel_hi:[1,0]
	v_pk_mul_f32 v[158:159], v[118:119], s[26:27] op_sel_hi:[1,0]
	v_cndmask_b32_e32 v147, v121, v157, vcc
	v_cndmask_b32_e32 v157, v120, v156, vcc
	v_cndmask_b32_e32 v156, v119, v159, vcc
	v_cndmask_b32_e32 v158, v118, v158, vcc
	v_cndmask_b32_e32 v159, v117, v163, vcc
	v_cndmask_b32_e32 v162, v116, v162, vcc
	v_cndmask_b32_e32 v163, v115, v165, vcc
	v_cndmask_b32_e32 v164, v114, v164, vcc
	v_cvt_pk_bf16_f32 v156, v158, v156
	v_cvt_pk_bf16_f32 v157, v157, v147
	v_cvt_pk_bf16_f32 v158, v164, v163
	v_cvt_pk_bf16_f32 v159, v162, v159
	global_store_dwordx4 v[160:161], v[156:159], off offset:256
	v_pk_mul_f32 v[162:163], v[48:49], s[26:27] op_sel_hi:[1,0]
	v_pk_mul_f32 v[164:165], v[46:47], s[26:27] op_sel_hi:[1,0]
	v_or_b32_e32 v156, 32, v146
	v_ashrrev_i32_e32 v157, 31, v156
	v_lshlrev_b64 v[156:157], 9, v[156:157]
	v_lshl_add_u64 v[156:157], v[150:151], 0, v[156:157]
	v_lshl_add_u64 v[160:161], v[156:157], 0, v[0:1]
	v_pk_mul_f32 v[156:157], v[52:53], s[26:27] op_sel_hi:[1,0]
	v_pk_mul_f32 v[158:159], v[50:51], s[26:27] op_sel_hi:[1,0]
	v_cndmask_b32_e32 v147, v53, v157, vcc
	v_cndmask_b32_e32 v157, v52, v156, vcc
	v_cndmask_b32_e32 v156, v51, v159, vcc
	v_cndmask_b32_e32 v158, v50, v158, vcc
	v_cndmask_b32_e32 v159, v49, v163, vcc
	v_cndmask_b32_e32 v162, v48, v162, vcc
	v_cndmask_b32_e32 v163, v47, v165, vcc
	v_cndmask_b32_e32 v164, v46, v164, vcc
	v_cvt_pk_bf16_f32 v156, v158, v156
	v_cvt_pk_bf16_f32 v157, v157, v147
	v_cvt_pk_bf16_f32 v158, v164, v163
	v_cvt_pk_bf16_f32 v159, v162, v159
	global_store_dwordx4 v[160:161], v[156:159], off
	v_pk_mul_f32 v[162:163], v[108:109], s[26:27] op_sel_hi:[1,0]
	v_pk_mul_f32 v[164:165], v[106:107], s[26:27] op_sel_hi:[1,0]
	v_pk_mul_f32 v[156:157], v[112:113], s[26:27] op_sel_hi:[1,0]
	v_pk_mul_f32 v[158:159], v[110:111], s[26:27] op_sel_hi:[1,0]
	v_cndmask_b32_e32 v147, v113, v157, vcc
	v_cndmask_b32_e32 v157, v112, v156, vcc
	v_cndmask_b32_e32 v156, v111, v159, vcc
	v_cndmask_b32_e32 v158, v110, v158, vcc
	v_cndmask_b32_e32 v159, v109, v163, vcc
	v_cndmask_b32_e32 v162, v108, v162, vcc
	v_cndmask_b32_e32 v163, v107, v165, vcc
	v_cndmask_b32_e32 v164, v106, v164, vcc
	v_cvt_pk_bf16_f32 v156, v158, v156
	v_cvt_pk_bf16_f32 v157, v157, v147
	v_cvt_pk_bf16_f32 v158, v164, v163
	v_cvt_pk_bf16_f32 v159, v162, v159
	global_store_dwordx4 v[160:161], v[156:159], off offset:256
	v_pk_mul_f32 v[160:161], v[40:41], s[26:27] op_sel_hi:[1,0]
	v_pk_mul_f32 v[162:163], v[38:39], s[26:27] op_sel_hi:[1,0]
	v_or_b32_e32 v156, 48, v146
	v_ashrrev_i32_e32 v157, 31, v156
	v_lshlrev_b64 v[156:157], 9, v[156:157]
	v_lshl_add_u64 v[150:151], v[150:151], 0, v[156:157]
	v_pk_mul_f32 v[156:157], v[44:45], s[26:27] op_sel_hi:[1,0]
	v_pk_mul_f32 v[158:159], v[42:43], s[26:27] op_sel_hi:[1,0]
	v_cndmask_b32_e32 v147, v45, v157, vcc
	v_cndmask_b32_e32 v157, v44, v156, vcc
	v_cndmask_b32_e32 v156, v43, v159, vcc
	v_cndmask_b32_e32 v158, v42, v158, vcc
	v_cndmask_b32_e32 v159, v41, v161, vcc
	v_cndmask_b32_e32 v160, v40, v160, vcc
	v_cndmask_b32_e32 v161, v39, v163, vcc
	v_cndmask_b32_e32 v162, v38, v162, vcc
	v_lshl_add_u64 v[150:151], v[150:151], 0, v[0:1]
	v_cvt_pk_bf16_f32 v156, v158, v156
	v_cvt_pk_bf16_f32 v157, v157, v147
	v_cvt_pk_bf16_f32 v158, v162, v161
	v_cvt_pk_bf16_f32 v159, v160, v159
	global_store_dwordx4 v[150:151], v[156:159], off
	v_pk_mul_f32 v[160:161], v[100:101], s[26:27] op_sel_hi:[1,0]
	v_pk_mul_f32 v[162:163], v[98:99], s[26:27] op_sel_hi:[1,0]
	v_pk_mul_f32 v[156:157], v[104:105], s[26:27] op_sel_hi:[1,0]
	v_pk_mul_f32 v[158:159], v[102:103], s[26:27] op_sel_hi:[1,0]
	v_cndmask_b32_e32 v147, v105, v157, vcc
	v_cndmask_b32_e32 v157, v104, v156, vcc
	v_cndmask_b32_e32 v156, v103, v159, vcc
	v_cndmask_b32_e32 v158, v102, v158, vcc
	v_cndmask_b32_e32 v159, v101, v161, vcc
	v_cndmask_b32_e32 v160, v100, v160, vcc
	v_cndmask_b32_e32 v161, v99, v163, vcc
	v_cndmask_b32_e32 v162, v98, v162, vcc
	v_cvt_pk_bf16_f32 v156, v158, v156
	v_cvt_pk_bf16_f32 v157, v157, v147
	v_cvt_pk_bf16_f32 v158, v162, v161
	v_cvt_pk_bf16_f32 v159, v160, v159
	global_store_dwordx4 v[150:151], v[156:159], off offset:256
	s_mov_b64 s[0:1], 0x10000
	v_pk_mul_f32 v[160:161], v[28:29], s[26:27] op_sel_hi:[1,0]
	v_pk_mul_f32 v[156:157], v[32:33], s[26:27] op_sel_hi:[1,0]
	v_pk_mul_f32 v[158:159], v[30:31], s[26:27] op_sel_hi:[1,0]
	v_lshl_add_u64 v[150:151], v[148:149], 0, s[0:1]
	v_pk_mul_f32 v[162:163], v[26:27], s[26:27] op_sel_hi:[1,0]
	v_cndmask_b32_e32 v147, v33, v157, vcc
	v_cndmask_b32_e32 v157, v32, v156, vcc
	v_cndmask_b32_e32 v156, v31, v159, vcc
	v_cndmask_b32_e32 v159, v29, v161, vcc
	v_cndmask_b32_e32 v160, v28, v160, vcc
	s_mov_b32 s0, 0x10000
	v_cndmask_b32_e32 v158, v30, v158, vcc
	v_cndmask_b32_e32 v161, v27, v163, vcc
	v_cndmask_b32_e32 v162, v26, v162, vcc
	v_cvt_pk_bf16_f32 v159, v160, v159
	v_add_co_u32_e64 v160, s[0:1], s0, v148
	v_cvt_pk_bf16_f32 v156, v158, v156
	v_cvt_pk_bf16_f32 v157, v157, v147
	v_cvt_pk_bf16_f32 v158, v162, v161
	v_addc_co_u32_e64 v161, s[0:1], 0, v149, s[0:1]
	global_store_dwordx4 v[160:161], v[156:159], off
	v_pk_mul_f32 v[160:161], v[92:93], s[26:27] op_sel_hi:[1,0]
	v_pk_mul_f32 v[162:163], v[90:91], s[26:27] op_sel_hi:[1,0]
	v_pk_mul_f32 v[156:157], v[96:97], s[26:27] op_sel_hi:[1,0]
	v_pk_mul_f32 v[158:159], v[94:95], s[26:27] op_sel_hi:[1,0]
	v_cndmask_b32_e32 v147, v97, v157, vcc
	v_cndmask_b32_e32 v157, v96, v156, vcc
	v_cndmask_b32_e32 v156, v95, v159, vcc
	v_cndmask_b32_e32 v158, v94, v158, vcc
	v_cndmask_b32_e32 v159, v93, v161, vcc
	v_cndmask_b32_e32 v160, v92, v160, vcc
	v_cndmask_b32_e32 v161, v91, v163, vcc
	v_cndmask_b32_e32 v162, v90, v162, vcc
	v_cvt_pk_bf16_f32 v156, v158, v156
	v_cvt_pk_bf16_f32 v157, v157, v147
	v_cvt_pk_bf16_f32 v158, v162, v161
	v_cvt_pk_bf16_f32 v159, v160, v159
	global_store_dwordx4 v[150:151], v[156:159], off offset:256
	s_mov_b64 s[0:1], 0x12000
	v_pk_mul_f32 v[160:161], v[20:21], s[26:27] op_sel_hi:[1,0]
	v_pk_mul_f32 v[156:157], v[24:25], s[26:27] op_sel_hi:[1,0]
	v_pk_mul_f32 v[158:159], v[22:23], s[26:27] op_sel_hi:[1,0]
	v_lshl_add_u64 v[150:151], v[148:149], 0, s[0:1]
	v_pk_mul_f32 v[162:163], v[18:19], s[26:27] op_sel_hi:[1,0]
	v_cndmask_b32_e32 v147, v25, v157, vcc
	v_cndmask_b32_e32 v157, v24, v156, vcc
	v_cndmask_b32_e32 v156, v23, v159, vcc
	v_cndmask_b32_e32 v159, v21, v161, vcc
	v_cndmask_b32_e32 v160, v20, v160, vcc
	s_mov_b32 s0, 0x12000
	v_cndmask_b32_e32 v158, v22, v158, vcc
	v_cndmask_b32_e32 v161, v19, v163, vcc
	v_cndmask_b32_e32 v162, v18, v162, vcc
	v_cvt_pk_bf16_f32 v159, v160, v159
	v_add_co_u32_e64 v160, s[0:1], s0, v148
	v_cvt_pk_bf16_f32 v156, v158, v156
	v_cvt_pk_bf16_f32 v157, v157, v147
	v_cvt_pk_bf16_f32 v158, v162, v161
	v_addc_co_u32_e64 v161, s[0:1], 0, v149, s[0:1]
	global_store_dwordx4 v[160:161], v[156:159], off
	v_pk_mul_f32 v[160:161], v[84:85], s[26:27] op_sel_hi:[1,0]
	v_pk_mul_f32 v[162:163], v[82:83], s[26:27] op_sel_hi:[1,0]
	v_pk_mul_f32 v[156:157], v[88:89], s[26:27] op_sel_hi:[1,0]
	v_pk_mul_f32 v[158:159], v[86:87], s[26:27] op_sel_hi:[1,0]
	v_cndmask_b32_e32 v147, v89, v157, vcc
	v_cndmask_b32_e32 v157, v88, v156, vcc
	v_cndmask_b32_e32 v156, v87, v159, vcc
	v_cndmask_b32_e32 v158, v86, v158, vcc
	v_cndmask_b32_e32 v159, v85, v161, vcc
	v_cndmask_b32_e32 v160, v84, v160, vcc
	v_cndmask_b32_e32 v161, v83, v163, vcc
	v_cndmask_b32_e32 v162, v82, v162, vcc
	v_cvt_pk_bf16_f32 v156, v158, v156
	v_cvt_pk_bf16_f32 v157, v157, v147
	v_cvt_pk_bf16_f32 v158, v162, v161
	v_cvt_pk_bf16_f32 v159, v160, v159
	global_store_dwordx4 v[150:151], v[156:159], off offset:256
	s_mov_b64 s[0:1], 0x14000
	v_pk_mul_f32 v[160:161], v[12:13], s[26:27] op_sel_hi:[1,0]
	v_pk_mul_f32 v[156:157], v[16:17], s[26:27] op_sel_hi:[1,0]
	v_pk_mul_f32 v[158:159], v[14:15], s[26:27] op_sel_hi:[1,0]
	v_lshl_add_u64 v[150:151], v[148:149], 0, s[0:1]
	v_pk_mul_f32 v[162:163], v[10:11], s[26:27] op_sel_hi:[1,0]
	v_cndmask_b32_e32 v147, v17, v157, vcc
	v_cndmask_b32_e32 v157, v16, v156, vcc
	v_cndmask_b32_e32 v156, v15, v159, vcc
	v_cndmask_b32_e32 v159, v13, v161, vcc
	v_cndmask_b32_e32 v160, v12, v160, vcc
	s_mov_b32 s0, 0x14000
	v_cndmask_b32_e32 v158, v14, v158, vcc
	v_cndmask_b32_e32 v161, v11, v163, vcc
	v_cndmask_b32_e32 v162, v10, v162, vcc
	v_cvt_pk_bf16_f32 v159, v160, v159
	v_add_co_u32_e64 v160, s[0:1], s0, v148
	v_cvt_pk_bf16_f32 v156, v158, v156
	v_cvt_pk_bf16_f32 v157, v157, v147
	v_cvt_pk_bf16_f32 v158, v162, v161
	v_addc_co_u32_e64 v161, s[0:1], 0, v149, s[0:1]
	global_store_dwordx4 v[160:161], v[156:159], off
	v_pk_mul_f32 v[160:161], v[76:77], s[26:27] op_sel_hi:[1,0]
	v_pk_mul_f32 v[162:163], v[74:75], s[26:27] op_sel_hi:[1,0]
	v_pk_mul_f32 v[156:157], v[80:81], s[26:27] op_sel_hi:[1,0]
	v_pk_mul_f32 v[158:159], v[78:79], s[26:27] op_sel_hi:[1,0]
	v_cndmask_b32_e32 v147, v81, v157, vcc
	v_cndmask_b32_e32 v157, v80, v156, vcc
	v_cndmask_b32_e32 v156, v79, v159, vcc
	v_cndmask_b32_e32 v158, v78, v158, vcc
	v_cndmask_b32_e32 v159, v77, v161, vcc
	v_cndmask_b32_e32 v160, v76, v160, vcc
	v_cndmask_b32_e32 v161, v75, v163, vcc
	v_cndmask_b32_e32 v162, v74, v162, vcc
	v_cvt_pk_bf16_f32 v156, v158, v156
	v_cvt_pk_bf16_f32 v157, v157, v147
	v_cvt_pk_bf16_f32 v158, v162, v161
	v_cvt_pk_bf16_f32 v159, v160, v159
	s_mov_b64 s[0:1], 0x16000
	global_store_dwordx4 v[150:151], v[156:159], off offset:256
	v_lshl_add_u64 v[160:161], v[148:149], 0, s[0:1]
	v_pk_mul_f32 v[150:151], v[8:9], s[26:27] op_sel_hi:[1,0]
	v_pk_mul_f32 v[156:157], v[6:7], s[26:27] op_sel_hi:[1,0]
	v_pk_mul_f32 v[158:159], v[4:5], s[26:27] op_sel_hi:[1,0]
	v_pk_mul_f32 v[162:163], v[2:3], s[26:27] op_sel_hi:[1,0]
	s_mov_b32 s0, 0x16000
	v_cndmask_b32_e32 v147, v9, v151, vcc
	v_cndmask_b32_e32 v150, v8, v150, vcc
	v_cndmask_b32_e32 v151, v7, v157, vcc
	v_cndmask_b32_e32 v156, v6, v156, vcc
	v_cndmask_b32_e32 v159, v5, v159, vcc
	v_cndmask_b32_e32 v164, v4, v158, vcc
	v_cndmask_b32_e32 v158, v3, v163, vcc
	v_cndmask_b32_e32 v162, v2, v162, vcc
	v_add_co_u32_e64 v148, s[0:1], s0, v148
	v_cvt_pk_bf16_f32 v156, v156, v151
	v_cvt_pk_bf16_f32 v157, v150, v147
	v_cvt_pk_bf16_f32 v158, v162, v158
	v_cvt_pk_bf16_f32 v159, v164, v159
	v_addc_co_u32_e64 v149, s[0:1], 0, v149, s[0:1]
	global_store_dwordx4 v[148:149], v[156:159], off
	v_pk_mul_f32 v[148:149], v[56:57], s[26:27] op_sel_hi:[1,0]
	v_pk_mul_f32 v[150:151], v[54:55], s[26:27] op_sel_hi:[1,0]
	v_pk_mul_f32 v[156:157], v[36:37], s[26:27] op_sel_hi:[1,0]
	v_pk_mul_f32 v[158:159], v[34:35], s[26:27] op_sel_hi:[1,0]
	v_cndmask_b32_e32 v147, v57, v149, vcc
	v_cndmask_b32_e32 v149, v56, v148, vcc
	v_cndmask_b32_e32 v148, v55, v151, vcc
	v_cndmask_b32_e32 v150, v54, v150, vcc
	v_cndmask_b32_e32 v151, v37, v157, vcc
	v_cndmask_b32_e32 v156, v36, v156, vcc
	v_cndmask_b32_e32 v157, v35, v159, vcc
	v_cndmask_b32_e32 v158, v34, v158, vcc
	v_cvt_pk_bf16_f32 v148, v150, v148
	v_cvt_pk_bf16_f32 v149, v149, v147
	v_cvt_pk_bf16_f32 v150, v158, v157
	v_cvt_pk_bf16_f32 v151, v156, v151
	global_store_dwordx4 v[160:161], v[148:151], off offset:256
	s_mov_b64 s[0:1], 0
.LBB0_111:
	s_andn2_b64 vcc, exec, s[0:1]
	s_cbranch_vccnz .LBB0_113
	s_mov_b32 s98, 8
	v_mul_f32_e32 v147, 0xbfb8aa3b, v70
	v_exp_f32_e32 v147, v147
	v_mul_f32_e32 v148, 0xbfb8aa3b, v71
	v_exp_f32_e32 v148, v148
	v_mul_f32_e32 v149, 0xbfb8aa3b, v73
	v_add_f32_e32 v147, 1.0, v147
	v_rcp_f32_e32 v156, v147
	v_add_f32_e32 v147, 1.0, v148
	v_mul_f32_e32 v148, 0xbfb8aa3b, v72
	v_exp_f32_e32 v148, v148
	v_exp_f32_e32 v149, v149
	v_rcp_f32_e32 v158, v147
	s_ashr_i32 s47, s46, 31
	v_add_f32_e32 v147, 1.0, v148
	v_mul_f32_e32 v148, 0xbfb8aa3b, v66
	v_exp_f32_e32 v148, v148
	v_rcp_f32_e32 v160, v147
	v_add_f32_e32 v147, 1.0, v149
	v_mul_f32_e32 v149, 0xbfb8aa3b, v67
	v_exp_f32_e32 v149, v149
	s_lshl_b64 s[0:1], s[18:19], 22
	v_rcp_f32_e32 v162, v147
	v_add_f32_e32 v147, 1.0, v148
	v_mul_f32_e32 v148, 0xbfb8aa3b, v68
	s_add_u32 s18, s14, s0
	v_exp_f32_e32 v148, v148
	s_addc_u32 s30, s15, s1
	s_lshl_b64 s[0:1], s[46:47], 17
	v_rcp_f32_e32 v157, v147
	v_add_f32_e32 v147, 1.0, v149
	v_mul_f32_e32 v149, 0xbfb8aa3b, v69
	s_add_u32 s0, s18, s0
	v_exp_f32_e32 v149, v149
	s_addc_u32 s1, s30, s1
	s_add_u32 s0, s0, s20
	v_rcp_f32_e32 v159, v147
	v_add_f32_e32 v147, 1.0, v148
	s_addc_u32 s1, s1, s21
	v_rcp_f32_e32 v161, v147
	v_lshl_add_u64 v[150:151], s[0:1], 0, v[138:139]
	v_add_f32_e32 v147, 1.0, v149
	s_mov_b32 s0, 0x43000000
	v_rcp_f32_e32 v163, v147
	v_mov_b64_e32 v[148:149], s[0:1]
	s_mov_b32 s0, 0x3f7f0000
	v_pk_fma_f32 v[156:157], v[156:157], s[0:1], v[148:149] op_sel_hi:[1,0,0]
	v_pk_fma_f32 v[158:159], v[158:159], s[0:1], v[148:149] op_sel_hi:[1,0,0]
	v_pk_fma_f32 v[160:161], v[160:161], s[0:1], v[148:149] op_sel_hi:[1,0,0]
	v_lshrrev_b32_e32 v147, 8, v157
	v_and_b32_e32 v157, 0xff00, v159
	v_or_b32_sdwa v147, v147, v157 dst_sel:DWORD dst_unused:UNUSED_PAD src0_sel:BYTE_0 src1_sel:DWORD
	v_lshlrev_b32_e32 v157, 8, v161
	v_pk_fma_f32 v[162:163], v[162:163], s[0:1], v[148:149] op_sel_hi:[1,0,0]
	v_and_b32_e32 v157, 0xff0000, v157
	v_or_b32_e32 v147, v147, v157
	v_lshlrev_b32_e32 v157, 16, v163
	v_mul_f32_e32 v127, 0xbfb8aa3b, v127
	v_and_b32_e32 v157, 0xff000000, v157
	v_exp_f32_e32 v127, v127
	v_mul_f32_e32 v128, 0xbfb8aa3b, v128
	v_lshrrev_b32_e32 v156, 8, v156
	v_and_b32_e32 v158, 0xff00, v158
	v_or_b32_e32 v157, v147, v157
	v_exp_f32_e32 v147, v128
	v_mul_f32_e32 v128, 0xbfb8aa3b, v129
	v_or_b32_sdwa v156, v156, v158 dst_sel:DWORD dst_unused:UNUSED_PAD src0_sel:BYTE_0 src1_sel:DWORD
	v_lshlrev_b32_e32 v158, 8, v160
	v_exp_f32_e32 v129, v128
	v_and_b32_e32 v158, 0xff0000, v158
	v_or_b32_e32 v156, v156, v158
	v_lshlrev_b32_e32 v158, 16, v162
	v_add_f32_e32 v127, 1.0, v127
	v_and_b32_e32 v158, 0xff000000, v158
	v_rcp_f32_e32 v128, v127
	v_add_f32_e32 v127, 1.0, v147
	v_mul_f32_e32 v122, 0xbfb8aa3b, v122
	v_mul_f32_e32 v126, 0xbfb8aa3b, v126
	v_or_b32_e32 v156, v156, v158
	v_rcp_f32_e32 v158, v127
	v_add_f32_e32 v127, 1.0, v129
	v_exp_f32_e32 v129, v122
	v_mul_f32_e32 v122, 0xbfb8aa3b, v123
	v_exp_f32_e32 v126, v126
	v_exp_f32_e32 v123, v122
	v_mul_f32_e32 v124, 0xbfb8aa3b, v124
	v_exp_f32_e32 v124, v124
	v_mul_f32_e32 v125, 0xbfb8aa3b, v125
	v_exp_f32_e32 v125, v125
	v_add_f32_e32 v126, 1.0, v126
	v_rcp_f32_e32 v122, v127
	v_add_f32_e32 v127, 1.0, v129
	v_add_f32_e32 v123, 1.0, v123
	v_rcp_f32_e32 v126, v126
	v_rcp_f32_e32 v127, v127
	v_rcp_f32_e32 v129, v123
	v_add_f32_e32 v123, 1.0, v124
	v_rcp_f32_e32 v159, v123
	v_add_f32_e32 v123, 1.0, v125
	v_rcp_f32_e32 v123, v123
	v_pk_fma_f32 v[124:125], v[126:127], s[0:1], v[148:149] op_sel_hi:[1,0,0]
	v_pk_fma_f32 v[126:127], v[128:129], s[0:1], v[148:149] op_sel_hi:[1,0,0]
	v_pk_fma_f32 v[128:129], v[158:159], s[0:1], v[148:149] op_sel_hi:[1,0,0]
	v_lshrrev_b32_e32 v124, 8, v124
	v_and_b32_e32 v126, 0xff00, v126
	v_pk_fma_f32 v[122:123], v[122:123], s[0:1], v[148:149] op_sel_hi:[1,0,0]
	v_lshrrev_b32_e32 v125, 8, v125
	v_and_b32_e32 v127, 0xff00, v127
	v_or_b32_sdwa v124, v124, v126 dst_sel:DWORD dst_unused:UNUSED_PAD src0_sel:BYTE_0 src1_sel:DWORD
	v_lshlrev_b32_e32 v126, 8, v129
	v_or_b32_sdwa v125, v125, v127 dst_sel:DWORD dst_unused:UNUSED_PAD src0_sel:BYTE_0 src1_sel:DWORD
	v_lshlrev_b32_e32 v127, 8, v128
	v_and_b32_e32 v126, 0xff0000, v126
	v_lshlrev_b32_e32 v123, 16, v123
	v_and_b32_e32 v127, 0xff0000, v127
	v_or_b32_e32 v125, v125, v126
	v_lshlrev_b32_e32 v122, 16, v122
	v_and_b32_e32 v123, 0xff000000, v123
	v_or_b32_e32 v124, v124, v127
	v_and_b32_e32 v122, 0xff000000, v122
	v_or_b32_e32 v159, v125, v123
	v_mul_f32_e32 v123, 0xbfb8aa3b, v63
	v_or_b32_e32 v158, v124, v122
	v_exp_f32_e32 v123, v123
	v_mul_f32_e32 v124, 0xbfb8aa3b, v64
	v_exp_f32_e32 v125, v124
	v_mul_f32_e32 v124, 0xbfb8aa3b, v65
	v_exp_f32_e32 v127, v124
	v_add_f32_e32 v123, 1.0, v123
	v_rcp_f32_e32 v124, v123
	v_add_f32_e32 v123, 1.0, v125
	v_rcp_f32_e32 v126, v123
	v_add_f32_e32 v123, 1.0, v127
	v_mul_f32_e32 v125, 0xbfb8aa3b, v58
	v_mul_f32_e32 v127, 0xbfb8aa3b, v59
	v_exp_f32_e32 v125, v125
	v_exp_f32_e32 v127, v127
	v_mul_f32_e32 v122, 0xbfb8aa3b, v62
	v_exp_f32_e32 v122, v122
	v_rcp_f32_e32 v128, v123
	v_add_f32_e32 v123, 1.0, v125
	v_add_f32_e32 v125, 1.0, v127
	v_mul_f32_e32 v127, 0xbfb8aa3b, v60
	v_exp_f32_e32 v127, v127
	v_mul_f32_e32 v129, 0xbfb8aa3b, v61
	v_exp_f32_e32 v129, v129
	v_add_f32_e32 v122, 1.0, v122
	v_rcp_f32_e32 v122, v122
	v_rcp_f32_e32 v123, v123
	v_rcp_f32_e32 v125, v125
	v_add_f32_e32 v127, 1.0, v127
	v_rcp_f32_e32 v127, v127
	v_add_f32_e32 v129, 1.0, v129
	v_rcp_f32_e32 v129, v129
	v_pk_fma_f32 v[122:123], v[122:123], s[0:1], v[148:149] op_sel_hi:[1,0,0]
	v_pk_fma_f32 v[124:125], v[124:125], s[0:1], v[148:149] op_sel_hi:[1,0,0]
	v_pk_fma_f32 v[126:127], v[126:127], s[0:1], v[148:149] op_sel_hi:[1,0,0]
	v_lshrrev_b32_e32 v122, 8, v122
	v_and_b32_e32 v124, 0xff00, v124
	v_lshrrev_b32_e32 v123, 8, v123
	v_and_b32_e32 v125, 0xff00, v125
	v_or_b32_sdwa v122, v122, v124 dst_sel:DWORD dst_unused:UNUSED_PAD src0_sel:BYTE_0 src1_sel:DWORD
	v_lshlrev_b32_e32 v124, 8, v127
	v_pk_fma_f32 v[128:129], v[128:129], s[0:1], v[148:149] op_sel_hi:[1,0,0]
	v_or_b32_sdwa v123, v123, v125 dst_sel:DWORD dst_unused:UNUSED_PAD src0_sel:BYTE_0 src1_sel:DWORD
	v_and_b32_e32 v124, 0xff0000, v124
	v_or_b32_e32 v123, v123, v124
	v_lshlrev_b32_e32 v124, 16, v129
	v_mul_f32_e32 v119, 0xbfb8aa3b, v119
	v_and_b32_e32 v124, 0xff000000, v124
	v_exp_f32_e32 v119, v119
	v_mul_f32_e32 v120, 0xbfb8aa3b, v120
	v_or_b32_e32 v123, v123, v124
	v_exp_f32_e32 v124, v120
	v_mul_f32_e32 v120, 0xbfb8aa3b, v121
	v_exp_f32_e32 v121, v120
	v_add_f32_e32 v119, 1.0, v119
	v_rcp_f32_e32 v120, v119
	v_add_f32_e32 v119, 1.0, v124
	v_mul_f32_e32 v114, 0xbfb8aa3b, v114
	v_mul_f32_e32 v118, 0xbfb8aa3b, v118
	v_rcp_f32_e32 v124, v119
	v_add_f32_e32 v119, 1.0, v121
	v_exp_f32_e32 v121, v114
	v_mul_f32_e32 v114, 0xbfb8aa3b, v115
	v_exp_f32_e32 v118, v118
	v_exp_f32_e32 v115, v114
	v_mul_f32_e32 v116, 0xbfb8aa3b, v116
	v_exp_f32_e32 v116, v116
	v_mul_f32_e32 v117, 0xbfb8aa3b, v117
	v_lshlrev_b32_e32 v125, 8, v126
	v_exp_f32_e32 v117, v117
	v_and_b32_e32 v125, 0xff0000, v125
	v_or_b32_e32 v122, v122, v125
	v_lshlrev_b32_e32 v125, 16, v128
	v_add_f32_e32 v118, 1.0, v118
	v_rcp_f32_e32 v114, v119
	v_add_f32_e32 v119, 1.0, v121
	v_add_f32_e32 v115, 1.0, v115
	v_and_b32_e32 v125, 0xff000000, v125
	v_rcp_f32_e32 v118, v118
	v_rcp_f32_e32 v119, v119
	v_rcp_f32_e32 v121, v115
	v_add_f32_e32 v115, 1.0, v116
	v_or_b32_e32 v122, v122, v125
	v_rcp_f32_e32 v125, v115
	v_add_f32_e32 v115, 1.0, v117
	v_rcp_f32_e32 v115, v115
	v_pk_fma_f32 v[116:117], v[118:119], s[0:1], v[148:149] op_sel_hi:[1,0,0]
	v_pk_fma_f32 v[118:119], v[120:121], s[0:1], v[148:149] op_sel_hi:[1,0,0]
	v_pk_fma_f32 v[120:121], v[124:125], s[0:1], v[148:149] op_sel_hi:[1,0,0]
	v_lshrrev_b32_e32 v116, 8, v116
	v_and_b32_e32 v118, 0xff00, v118
	v_pk_fma_f32 v[114:115], v[114:115], s[0:1], v[148:149] op_sel_hi:[1,0,0]
	v_lshrrev_b32_e32 v117, 8, v117
	v_and_b32_e32 v119, 0xff00, v119
	v_or_b32_sdwa v116, v116, v118 dst_sel:DWORD dst_unused:UNUSED_PAD src0_sel:BYTE_0 src1_sel:DWORD
	v_lshlrev_b32_e32 v118, 8, v121
	v_or_b32_sdwa v117, v117, v119 dst_sel:DWORD dst_unused:UNUSED_PAD src0_sel:BYTE_0 src1_sel:DWORD
	v_lshlrev_b32_e32 v119, 8, v120
	v_and_b32_e32 v118, 0xff0000, v118
	v_lshlrev_b32_e32 v115, 16, v115
	v_and_b32_e32 v119, 0xff0000, v119
	v_or_b32_e32 v117, v117, v118
	v_lshlrev_b32_e32 v114, 16, v114
	v_and_b32_e32 v115, 0xff000000, v115
	v_or_b32_e32 v116, v116, v119
	v_and_b32_e32 v114, 0xff000000, v114
	v_or_b32_e32 v125, v117, v115
	v_mul_f32_e32 v115, 0xbfb8aa3b, v51
	v_or_b32_e32 v124, v116, v114
	v_exp_f32_e32 v115, v115
	v_mul_f32_e32 v116, 0xbfb8aa3b, v52
	v_exp_f32_e32 v117, v116
	v_mul_f32_e32 v116, 0xbfb8aa3b, v53
	v_exp_f32_e32 v119, v116
	v_add_f32_e32 v115, 1.0, v115
	v_rcp_f32_e32 v116, v115
	v_add_f32_e32 v115, 1.0, v117
	v_rcp_f32_e32 v118, v115
	v_add_f32_e32 v115, 1.0, v119
	v_mul_f32_e32 v117, 0xbfb8aa3b, v46
	v_mul_f32_e32 v119, 0xbfb8aa3b, v47
	v_exp_f32_e32 v117, v117
	v_exp_f32_e32 v119, v119
	v_mul_f32_e32 v114, 0xbfb8aa3b, v50
	v_exp_f32_e32 v114, v114
	v_rcp_f32_e32 v120, v115
	v_add_f32_e32 v115, 1.0, v117
	v_add_f32_e32 v117, 1.0, v119
	v_mul_f32_e32 v119, 0xbfb8aa3b, v48
	v_exp_f32_e32 v119, v119
	v_mul_f32_e32 v121, 0xbfb8aa3b, v49
	v_exp_f32_e32 v121, v121
	v_add_f32_e32 v114, 1.0, v114
	v_rcp_f32_e32 v114, v114
	v_rcp_f32_e32 v115, v115
	v_rcp_f32_e32 v117, v117
	v_add_f32_e32 v119, 1.0, v119
	v_rcp_f32_e32 v119, v119
	v_add_f32_e32 v121, 1.0, v121
	v_rcp_f32_e32 v121, v121
	v_pk_fma_f32 v[114:115], v[114:115], s[0:1], v[148:149] op_sel_hi:[1,0,0]
	v_pk_fma_f32 v[116:117], v[116:117], s[0:1], v[148:149] op_sel_hi:[1,0,0]
	v_pk_fma_f32 v[118:119], v[118:119], s[0:1], v[148:149] op_sel_hi:[1,0,0]
	v_lshrrev_b32_e32 v114, 8, v114
	v_and_b32_e32 v116, 0xff00, v116
	v_lshrrev_b32_e32 v115, 8, v115
	v_and_b32_e32 v117, 0xff00, v117
	v_or_b32_sdwa v114, v114, v116 dst_sel:DWORD dst_unused:UNUSED_PAD src0_sel:BYTE_0 src1_sel:DWORD
	v_lshlrev_b32_e32 v116, 8, v119
	v_pk_fma_f32 v[120:121], v[120:121], s[0:1], v[148:149] op_sel_hi:[1,0,0]
	v_or_b32_sdwa v115, v115, v117 dst_sel:DWORD dst_unused:UNUSED_PAD src0_sel:BYTE_0 src1_sel:DWORD
	v_and_b32_e32 v116, 0xff0000, v116
	v_or_b32_e32 v115, v115, v116
	v_lshlrev_b32_e32 v116, 16, v121
	v_mul_f32_e32 v111, 0xbfb8aa3b, v111
	v_and_b32_e32 v116, 0xff000000, v116
	v_exp_f32_e32 v111, v111
	v_mul_f32_e32 v112, 0xbfb8aa3b, v112
	v_or_b32_e32 v115, v115, v116
	v_exp_f32_e32 v116, v112
	v_mul_f32_e32 v112, 0xbfb8aa3b, v113
	v_exp_f32_e32 v113, v112
	v_add_f32_e32 v111, 1.0, v111
	v_rcp_f32_e32 v112, v111
	v_add_f32_e32 v111, 1.0, v116
	v_mul_f32_e32 v106, 0xbfb8aa3b, v106
	v_mul_f32_e32 v110, 0xbfb8aa3b, v110
	v_rcp_f32_e32 v116, v111
	v_add_f32_e32 v111, 1.0, v113
	v_exp_f32_e32 v113, v106
	v_mul_f32_e32 v106, 0xbfb8aa3b, v107
	v_exp_f32_e32 v110, v110
	v_exp_f32_e32 v107, v106
	v_mul_f32_e32 v108, 0xbfb8aa3b, v108
	v_exp_f32_e32 v108, v108
	v_mul_f32_e32 v109, 0xbfb8aa3b, v109
	v_lshlrev_b32_e32 v117, 8, v118
	v_exp_f32_e32 v109, v109
	v_and_b32_e32 v117, 0xff0000, v117
	v_or_b32_e32 v114, v114, v117
	v_lshlrev_b32_e32 v117, 16, v120
	v_add_f32_e32 v110, 1.0, v110
	v_rcp_f32_e32 v106, v111
	v_add_f32_e32 v111, 1.0, v113
	v_add_f32_e32 v107, 1.0, v107
	v_and_b32_e32 v117, 0xff000000, v117
	v_rcp_f32_e32 v110, v110
	v_rcp_f32_e32 v111, v111
	v_rcp_f32_e32 v113, v107
	v_add_f32_e32 v107, 1.0, v108
	v_or_b32_e32 v114, v114, v117
	v_rcp_f32_e32 v117, v107
	v_add_f32_e32 v107, 1.0, v109
	v_rcp_f32_e32 v107, v107
	v_pk_fma_f32 v[108:109], v[110:111], s[0:1], v[148:149] op_sel_hi:[1,0,0]
	v_pk_fma_f32 v[110:111], v[112:113], s[0:1], v[148:149] op_sel_hi:[1,0,0]
	v_pk_fma_f32 v[112:113], v[116:117], s[0:1], v[148:149] op_sel_hi:[1,0,0]
	v_lshrrev_b32_e32 v108, 8, v108
	v_and_b32_e32 v110, 0xff00, v110
	v_pk_fma_f32 v[106:107], v[106:107], s[0:1], v[148:149] op_sel_hi:[1,0,0]
	v_lshrrev_b32_e32 v109, 8, v109
	v_and_b32_e32 v111, 0xff00, v111
	v_or_b32_sdwa v108, v108, v110 dst_sel:DWORD dst_unused:UNUSED_PAD src0_sel:BYTE_0 src1_sel:DWORD
	v_lshlrev_b32_e32 v110, 8, v113
	v_or_b32_sdwa v109, v109, v111 dst_sel:DWORD dst_unused:UNUSED_PAD src0_sel:BYTE_0 src1_sel:DWORD
	v_lshlrev_b32_e32 v111, 8, v112
	v_and_b32_e32 v110, 0xff0000, v110
	v_lshlrev_b32_e32 v107, 16, v107
	v_and_b32_e32 v111, 0xff0000, v111
	v_or_b32_e32 v109, v109, v110
	v_lshlrev_b32_e32 v106, 16, v106
	v_and_b32_e32 v107, 0xff000000, v107
	v_or_b32_e32 v108, v108, v111
	v_and_b32_e32 v106, 0xff000000, v106
	v_or_b32_e32 v117, v109, v107
	v_mul_f32_e32 v107, 0xbfb8aa3b, v43
	v_or_b32_e32 v116, v108, v106
	v_exp_f32_e32 v107, v107
	v_mul_f32_e32 v108, 0xbfb8aa3b, v44
	v_exp_f32_e32 v109, v108
	v_mul_f32_e32 v108, 0xbfb8aa3b, v45
	v_exp_f32_e32 v111, v108
	v_add_f32_e32 v107, 1.0, v107
	v_rcp_f32_e32 v108, v107
	v_add_f32_e32 v107, 1.0, v109
	v_rcp_f32_e32 v110, v107
	v_add_f32_e32 v107, 1.0, v111
	v_mul_f32_e32 v109, 0xbfb8aa3b, v38
	v_mul_f32_e32 v111, 0xbfb8aa3b, v39
	v_exp_f32_e32 v109, v109
	v_exp_f32_e32 v111, v111
	v_mul_f32_e32 v106, 0xbfb8aa3b, v42
	v_exp_f32_e32 v106, v106
	v_rcp_f32_e32 v112, v107
	v_add_f32_e32 v107, 1.0, v109
	v_add_f32_e32 v109, 1.0, v111
	v_mul_f32_e32 v111, 0xbfb8aa3b, v40
	v_exp_f32_e32 v111, v111
	v_mul_f32_e32 v113, 0xbfb8aa3b, v41
	v_exp_f32_e32 v113, v113
	v_add_f32_e32 v106, 1.0, v106
	v_rcp_f32_e32 v106, v106
	v_rcp_f32_e32 v107, v107
	v_rcp_f32_e32 v109, v109
	v_add_f32_e32 v111, 1.0, v111
	v_rcp_f32_e32 v111, v111
	v_add_f32_e32 v113, 1.0, v113
	v_rcp_f32_e32 v113, v113
	v_pk_fma_f32 v[106:107], v[106:107], s[0:1], v[148:149] op_sel_hi:[1,0,0]
	v_pk_fma_f32 v[108:109], v[108:109], s[0:1], v[148:149] op_sel_hi:[1,0,0]
	v_pk_fma_f32 v[110:111], v[110:111], s[0:1], v[148:149] op_sel_hi:[1,0,0]
	v_lshrrev_b32_e32 v106, 8, v106
	v_and_b32_e32 v108, 0xff00, v108
	v_lshrrev_b32_e32 v107, 8, v107
	v_and_b32_e32 v109, 0xff00, v109
	v_or_b32_sdwa v106, v106, v108 dst_sel:DWORD dst_unused:UNUSED_PAD src0_sel:BYTE_0 src1_sel:DWORD
	v_lshlrev_b32_e32 v108, 8, v111
	v_pk_fma_f32 v[112:113], v[112:113], s[0:1], v[148:149] op_sel_hi:[1,0,0]
	v_or_b32_sdwa v107, v107, v109 dst_sel:DWORD dst_unused:UNUSED_PAD src0_sel:BYTE_0 src1_sel:DWORD
	v_and_b32_e32 v108, 0xff0000, v108
	v_or_b32_e32 v107, v107, v108
	v_lshlrev_b32_e32 v108, 16, v113
	v_mul_f32_e32 v103, 0xbfb8aa3b, v103
	v_and_b32_e32 v108, 0xff000000, v108
	v_exp_f32_e32 v103, v103
	v_mul_f32_e32 v104, 0xbfb8aa3b, v104
	v_or_b32_e32 v107, v107, v108
	v_exp_f32_e32 v108, v104
	v_mul_f32_e32 v104, 0xbfb8aa3b, v105
	v_exp_f32_e32 v105, v104
	v_add_f32_e32 v103, 1.0, v103
	v_rcp_f32_e32 v104, v103
	v_add_f32_e32 v103, 1.0, v108
	v_mul_f32_e32 v98, 0xbfb8aa3b, v98
	v_mul_f32_e32 v102, 0xbfb8aa3b, v102
	v_rcp_f32_e32 v108, v103
	v_add_f32_e32 v103, 1.0, v105
	v_exp_f32_e32 v105, v98
	v_mul_f32_e32 v98, 0xbfb8aa3b, v99
	v_exp_f32_e32 v102, v102
	v_exp_f32_e32 v99, v98
	v_mul_f32_e32 v100, 0xbfb8aa3b, v100
	v_exp_f32_e32 v100, v100
	v_mul_f32_e32 v101, 0xbfb8aa3b, v101
	v_lshlrev_b32_e32 v109, 8, v110
	v_exp_f32_e32 v101, v101
	v_and_b32_e32 v109, 0xff0000, v109
	v_or_b32_e32 v106, v106, v109
	v_lshlrev_b32_e32 v109, 16, v112
	v_add_f32_e32 v102, 1.0, v102
	v_rcp_f32_e32 v98, v103
	v_add_f32_e32 v103, 1.0, v105
	v_add_f32_e32 v99, 1.0, v99
	v_and_b32_e32 v109, 0xff000000, v109
	v_rcp_f32_e32 v102, v102
	v_rcp_f32_e32 v103, v103
	v_rcp_f32_e32 v105, v99
	v_add_f32_e32 v99, 1.0, v100
	v_or_b32_e32 v106, v106, v109
	v_rcp_f32_e32 v109, v99
	v_add_f32_e32 v99, 1.0, v101
	v_rcp_f32_e32 v99, v99
	v_pk_fma_f32 v[100:101], v[102:103], s[0:1], v[148:149] op_sel_hi:[1,0,0]
	v_pk_fma_f32 v[102:103], v[104:105], s[0:1], v[148:149] op_sel_hi:[1,0,0]
	v_pk_fma_f32 v[104:105], v[108:109], s[0:1], v[148:149] op_sel_hi:[1,0,0]
	v_lshrrev_b32_e32 v100, 8, v100
	v_and_b32_e32 v102, 0xff00, v102
	v_pk_fma_f32 v[98:99], v[98:99], s[0:1], v[148:149] op_sel_hi:[1,0,0]
	v_lshrrev_b32_e32 v101, 8, v101
	v_and_b32_e32 v103, 0xff00, v103
	v_or_b32_sdwa v100, v100, v102 dst_sel:DWORD dst_unused:UNUSED_PAD src0_sel:BYTE_0 src1_sel:DWORD
	v_lshlrev_b32_e32 v102, 8, v105
	v_or_b32_sdwa v101, v101, v103 dst_sel:DWORD dst_unused:UNUSED_PAD src0_sel:BYTE_0 src1_sel:DWORD
	v_lshlrev_b32_e32 v103, 8, v104
	v_and_b32_e32 v102, 0xff0000, v102
	v_lshlrev_b32_e32 v99, 16, v99
	v_and_b32_e32 v103, 0xff0000, v103
	v_or_b32_e32 v101, v101, v102
	v_lshlrev_b32_e32 v98, 16, v98
	v_and_b32_e32 v99, 0xff000000, v99
	v_or_b32_e32 v100, v100, v103
	v_and_b32_e32 v98, 0xff000000, v98
	v_or_b32_e32 v109, v101, v99
	v_mul_f32_e32 v99, 0xbfb8aa3b, v31
	v_or_b32_e32 v108, v100, v98
	v_exp_f32_e32 v99, v99
	v_mul_f32_e32 v100, 0xbfb8aa3b, v32
	v_exp_f32_e32 v101, v100
	v_mul_f32_e32 v100, 0xbfb8aa3b, v33
	v_exp_f32_e32 v103, v100
	v_add_f32_e32 v99, 1.0, v99
	v_rcp_f32_e32 v100, v99
	v_add_f32_e32 v99, 1.0, v101
	v_rcp_f32_e32 v102, v99
	v_add_f32_e32 v99, 1.0, v103
	v_mul_f32_e32 v101, 0xbfb8aa3b, v26
	v_mul_f32_e32 v103, 0xbfb8aa3b, v27
	v_exp_f32_e32 v101, v101
	v_exp_f32_e32 v103, v103
	v_mul_f32_e32 v98, 0xbfb8aa3b, v30
	v_exp_f32_e32 v98, v98
	v_rcp_f32_e32 v104, v99
	v_add_f32_e32 v99, 1.0, v101
	v_add_f32_e32 v101, 1.0, v103
	v_mul_f32_e32 v103, 0xbfb8aa3b, v28
	v_exp_f32_e32 v103, v103
	v_mul_f32_e32 v105, 0xbfb8aa3b, v29
	v_exp_f32_e32 v105, v105
	v_add_f32_e32 v98, 1.0, v98
	v_rcp_f32_e32 v98, v98
	v_rcp_f32_e32 v99, v99
	v_rcp_f32_e32 v101, v101
	v_add_f32_e32 v103, 1.0, v103
	v_rcp_f32_e32 v103, v103
	v_add_f32_e32 v105, 1.0, v105
	v_rcp_f32_e32 v105, v105
	v_pk_fma_f32 v[98:99], v[98:99], s[0:1], v[148:149] op_sel_hi:[1,0,0]
	v_pk_fma_f32 v[100:101], v[100:101], s[0:1], v[148:149] op_sel_hi:[1,0,0]
	v_pk_fma_f32 v[102:103], v[102:103], s[0:1], v[148:149] op_sel_hi:[1,0,0]
	v_lshrrev_b32_e32 v98, 8, v98
	v_and_b32_e32 v100, 0xff00, v100
	v_lshrrev_b32_e32 v99, 8, v99
	v_and_b32_e32 v101, 0xff00, v101
	v_or_b32_sdwa v98, v98, v100 dst_sel:DWORD dst_unused:UNUSED_PAD src0_sel:BYTE_0 src1_sel:DWORD
	v_lshlrev_b32_e32 v100, 8, v103
	v_pk_fma_f32 v[104:105], v[104:105], s[0:1], v[148:149] op_sel_hi:[1,0,0]
	v_or_b32_sdwa v99, v99, v101 dst_sel:DWORD dst_unused:UNUSED_PAD src0_sel:BYTE_0 src1_sel:DWORD
	v_and_b32_e32 v100, 0xff0000, v100
	v_or_b32_e32 v99, v99, v100
	v_lshlrev_b32_e32 v100, 16, v105
	v_mul_f32_e32 v95, 0xbfb8aa3b, v95
	v_and_b32_e32 v100, 0xff000000, v100
	v_exp_f32_e32 v95, v95
	v_mul_f32_e32 v96, 0xbfb8aa3b, v96
	v_or_b32_e32 v99, v99, v100
	v_exp_f32_e32 v100, v96
	v_mul_f32_e32 v96, 0xbfb8aa3b, v97
	v_exp_f32_e32 v97, v96
	v_add_f32_e32 v95, 1.0, v95
	v_rcp_f32_e32 v96, v95
	v_add_f32_e32 v95, 1.0, v100
	v_mul_f32_e32 v90, 0xbfb8aa3b, v90
	v_mul_f32_e32 v94, 0xbfb8aa3b, v94
	v_rcp_f32_e32 v100, v95
	v_add_f32_e32 v95, 1.0, v97
	v_exp_f32_e32 v97, v90
	v_mul_f32_e32 v90, 0xbfb8aa3b, v91
	v_exp_f32_e32 v94, v94
	v_exp_f32_e32 v91, v90
	v_mul_f32_e32 v92, 0xbfb8aa3b, v92
	v_exp_f32_e32 v92, v92
	v_mul_f32_e32 v93, 0xbfb8aa3b, v93
	v_lshlrev_b32_e32 v101, 8, v102
	v_exp_f32_e32 v93, v93
	v_and_b32_e32 v101, 0xff0000, v101
	v_or_b32_e32 v98, v98, v101
	v_lshlrev_b32_e32 v101, 16, v104
	v_add_f32_e32 v94, 1.0, v94
	v_rcp_f32_e32 v90, v95
	v_add_f32_e32 v95, 1.0, v97
	v_add_f32_e32 v91, 1.0, v91
	v_and_b32_e32 v101, 0xff000000, v101
	v_rcp_f32_e32 v94, v94
	v_rcp_f32_e32 v95, v95
	v_rcp_f32_e32 v97, v91
	v_add_f32_e32 v91, 1.0, v92
	v_or_b32_e32 v98, v98, v101
	v_rcp_f32_e32 v101, v91
	v_add_f32_e32 v91, 1.0, v93
	v_rcp_f32_e32 v91, v91
	v_pk_fma_f32 v[92:93], v[94:95], s[0:1], v[148:149] op_sel_hi:[1,0,0]
	v_pk_fma_f32 v[94:95], v[96:97], s[0:1], v[148:149] op_sel_hi:[1,0,0]
	v_pk_fma_f32 v[96:97], v[100:101], s[0:1], v[148:149] op_sel_hi:[1,0,0]
	v_lshrrev_b32_e32 v92, 8, v92
	v_and_b32_e32 v94, 0xff00, v94
	v_pk_fma_f32 v[90:91], v[90:91], s[0:1], v[148:149] op_sel_hi:[1,0,0]
	v_lshrrev_b32_e32 v93, 8, v93
	v_and_b32_e32 v95, 0xff00, v95
	v_or_b32_sdwa v92, v92, v94 dst_sel:DWORD dst_unused:UNUSED_PAD src0_sel:BYTE_0 src1_sel:DWORD
	v_lshlrev_b32_e32 v94, 8, v97
	v_or_b32_sdwa v93, v93, v95 dst_sel:DWORD dst_unused:UNUSED_PAD src0_sel:BYTE_0 src1_sel:DWORD
	v_and_b32_e32 v94, 0xff0000, v94
	v_lshlrev_b32_e32 v91, 16, v91
	v_or_b32_e32 v93, v93, v94
	v_and_b32_e32 v91, 0xff000000, v91
	v_lshlrev_b32_e32 v95, 8, v96
	v_or_b32_e32 v101, v93, v91
	v_mul_f32_e32 v93, 0xbfb8aa3b, v23
	v_and_b32_e32 v95, 0xff0000, v95
	v_exp_f32_e32 v93, v93
	v_mul_f32_e32 v94, 0xbfb8aa3b, v24
	v_or_b32_e32 v92, v92, v95
	v_exp_f32_e32 v95, v94
	v_mul_f32_e32 v94, 0xbfb8aa3b, v25
	v_exp_f32_e32 v97, v94
	v_add_f32_e32 v93, 1.0, v93
	v_rcp_f32_e32 v94, v93
	v_add_f32_e32 v93, 1.0, v95
	v_rcp_f32_e32 v96, v93
	v_add_f32_e32 v93, 1.0, v97
	v_mul_f32_e32 v95, 0xbfb8aa3b, v18
	v_mul_f32_e32 v97, 0xbfb8aa3b, v19
	v_lshlrev_b32_e32 v90, 16, v90
	v_exp_f32_e32 v95, v95
	v_exp_f32_e32 v97, v97
	v_and_b32_e32 v90, 0xff000000, v90
	v_or_b32_e32 v100, v92, v90
	v_add_co_u32_e32 v90, vcc, s27, v150
	v_mul_f32_e32 v92, 0xbfb8aa3b, v22
	s_nop 0
	v_addc_co_u32_e32 v91, vcc, 0, v151, vcc
	v_exp_f32_e32 v92, v92
	global_store_dwordx4 v[90:91], v[98:101], off
	v_mul_f32_e32 v87, 0xbfb8aa3b, v87
	v_exp_f32_e32 v87, v87
	v_rcp_f32_e32 v98, v93
	v_add_f32_e32 v93, 1.0, v95
	v_add_f32_e32 v95, 1.0, v97
	v_mul_f32_e32 v97, 0xbfb8aa3b, v20
	v_exp_f32_e32 v97, v97
	v_mul_f32_e32 v99, 0xbfb8aa3b, v21
	v_exp_f32_e32 v99, v99
	v_add_f32_e32 v92, 1.0, v92
	v_rcp_f32_e32 v92, v92
	v_rcp_f32_e32 v93, v93
	v_rcp_f32_e32 v95, v95
	v_add_f32_e32 v97, 1.0, v97
	v_rcp_f32_e32 v97, v97
	v_add_f32_e32 v99, 1.0, v99
	v_rcp_f32_e32 v99, v99
	v_pk_fma_f32 v[92:93], v[92:93], s[0:1], v[148:149] op_sel_hi:[1,0,0]
	v_pk_fma_f32 v[94:95], v[94:95], s[0:1], v[148:149] op_sel_hi:[1,0,0]
	v_pk_fma_f32 v[96:97], v[96:97], s[0:1], v[148:149] op_sel_hi:[1,0,0]
	v_lshrrev_b32_e32 v92, 8, v92
	v_and_b32_e32 v94, 0xff00, v94
	v_lshrrev_b32_e32 v93, 8, v93
	v_and_b32_e32 v95, 0xff00, v95
	v_or_b32_sdwa v92, v92, v94 dst_sel:DWORD dst_unused:UNUSED_PAD src0_sel:BYTE_0 src1_sel:DWORD
	v_lshlrev_b32_e32 v94, 8, v97
	v_pk_fma_f32 v[98:99], v[98:99], s[0:1], v[148:149] op_sel_hi:[1,0,0]
	v_or_b32_sdwa v93, v93, v95 dst_sel:DWORD dst_unused:UNUSED_PAD src0_sel:BYTE_0 src1_sel:DWORD
	v_and_b32_e32 v94, 0xff0000, v94
	v_or_b32_e32 v93, v93, v94
	v_lshlrev_b32_e32 v94, 16, v99
	v_and_b32_e32 v94, 0xff000000, v94
	v_mul_f32_e32 v88, 0xbfb8aa3b, v88
	v_or_b32_e32 v93, v93, v94
	v_exp_f32_e32 v94, v88
	v_mul_f32_e32 v88, 0xbfb8aa3b, v89
	v_exp_f32_e32 v89, v88
	v_add_f32_e32 v87, 1.0, v87
	v_rcp_f32_e32 v88, v87
	v_add_f32_e32 v87, 1.0, v94
	v_mul_f32_e32 v82, 0xbfb8aa3b, v82
	v_mul_f32_e32 v86, 0xbfb8aa3b, v86
	v_rcp_f32_e32 v94, v87
	v_add_f32_e32 v87, 1.0, v89
	v_exp_f32_e32 v89, v82
	v_mul_f32_e32 v82, 0xbfb8aa3b, v83
	v_exp_f32_e32 v86, v86
	v_exp_f32_e32 v83, v82
	v_mul_f32_e32 v84, 0xbfb8aa3b, v84
	v_exp_f32_e32 v84, v84
	v_mul_f32_e32 v85, 0xbfb8aa3b, v85
	v_lshlrev_b32_e32 v95, 8, v96
	v_exp_f32_e32 v85, v85
	v_and_b32_e32 v95, 0xff0000, v95
	v_or_b32_e32 v92, v92, v95
	v_lshlrev_b32_e32 v95, 16, v98
	v_add_f32_e32 v86, 1.0, v86
	v_rcp_f32_e32 v82, v87
	v_add_f32_e32 v87, 1.0, v89
	v_add_f32_e32 v83, 1.0, v83
	v_and_b32_e32 v95, 0xff000000, v95
	v_rcp_f32_e32 v86, v86
	v_rcp_f32_e32 v87, v87
	v_rcp_f32_e32 v89, v83
	v_add_f32_e32 v83, 1.0, v84
	v_or_b32_e32 v92, v92, v95
	v_rcp_f32_e32 v95, v83
	v_add_f32_e32 v83, 1.0, v85
	v_rcp_f32_e32 v83, v83
	v_pk_fma_f32 v[84:85], v[86:87], s[0:1], v[148:149] op_sel_hi:[1,0,0]
	v_pk_fma_f32 v[86:87], v[88:89], s[0:1], v[148:149] op_sel_hi:[1,0,0]
	v_pk_fma_f32 v[88:89], v[94:95], s[0:1], v[148:149] op_sel_hi:[1,0,0]
	v_lshrrev_b32_e32 v84, 8, v84
	v_and_b32_e32 v86, 0xff00, v86
	v_pk_fma_f32 v[82:83], v[82:83], s[0:1], v[148:149] op_sel_hi:[1,0,0]
	v_lshrrev_b32_e32 v85, 8, v85
	v_and_b32_e32 v87, 0xff00, v87
	v_or_b32_sdwa v84, v84, v86 dst_sel:DWORD dst_unused:UNUSED_PAD src0_sel:BYTE_0 src1_sel:DWORD
	v_lshlrev_b32_e32 v86, 8, v89
	v_or_b32_sdwa v85, v85, v87 dst_sel:DWORD dst_unused:UNUSED_PAD src0_sel:BYTE_0 src1_sel:DWORD
	v_lshlrev_b32_e32 v87, 8, v88
	v_and_b32_e32 v86, 0xff0000, v86
	v_lshlrev_b32_e32 v83, 16, v83
	v_and_b32_e32 v87, 0xff0000, v87
	v_or_b32_e32 v85, v85, v86
	v_lshlrev_b32_e32 v82, 16, v82
	v_and_b32_e32 v83, 0xff000000, v83
	v_or_b32_e32 v84, v84, v87
	v_and_b32_e32 v82, 0xff000000, v82
	v_or_b32_e32 v95, v85, v83
	v_mul_f32_e32 v83, 0xbfb8aa3b, v15
	v_or_b32_e32 v94, v84, v82
	v_exp_f32_e32 v83, v83
	v_mul_f32_e32 v84, 0xbfb8aa3b, v16
	v_exp_f32_e32 v85, v84
	v_mul_f32_e32 v84, 0xbfb8aa3b, v17
	v_exp_f32_e32 v87, v84
	v_add_f32_e32 v83, 1.0, v83
	v_rcp_f32_e32 v84, v83
	v_add_f32_e32 v83, 1.0, v85
	v_rcp_f32_e32 v86, v83
	v_add_f32_e32 v83, 1.0, v87
	v_mul_f32_e32 v85, 0xbfb8aa3b, v10
	v_mul_f32_e32 v87, 0xbfb8aa3b, v11
	v_exp_f32_e32 v85, v85
	v_exp_f32_e32 v87, v87
	v_mul_f32_e32 v82, 0xbfb8aa3b, v14
	v_exp_f32_e32 v82, v82
	v_rcp_f32_e32 v88, v83
	v_add_f32_e32 v83, 1.0, v85
	v_add_f32_e32 v85, 1.0, v87
	v_mul_f32_e32 v87, 0xbfb8aa3b, v12
	v_exp_f32_e32 v87, v87
	v_mul_f32_e32 v89, 0xbfb8aa3b, v13
	v_exp_f32_e32 v89, v89
	v_add_f32_e32 v82, 1.0, v82
	v_rcp_f32_e32 v82, v82
	v_rcp_f32_e32 v83, v83
	v_rcp_f32_e32 v85, v85
	v_add_f32_e32 v87, 1.0, v87
	v_rcp_f32_e32 v87, v87
	v_add_f32_e32 v89, 1.0, v89
	v_rcp_f32_e32 v89, v89
	v_pk_fma_f32 v[82:83], v[82:83], s[0:1], v[148:149] op_sel_hi:[1,0,0]
	v_pk_fma_f32 v[84:85], v[84:85], s[0:1], v[148:149] op_sel_hi:[1,0,0]
	v_pk_fma_f32 v[86:87], v[86:87], s[0:1], v[148:149] op_sel_hi:[1,0,0]
	v_lshrrev_b32_e32 v82, 8, v82
	v_and_b32_e32 v84, 0xff00, v84
	v_lshrrev_b32_e32 v83, 8, v83
	v_and_b32_e32 v85, 0xff00, v85
	v_or_b32_sdwa v82, v82, v84 dst_sel:DWORD dst_unused:UNUSED_PAD src0_sel:BYTE_0 src1_sel:DWORD
	v_lshlrev_b32_e32 v84, 8, v87
	v_pk_fma_f32 v[88:89], v[88:89], s[0:1], v[148:149] op_sel_hi:[1,0,0]
	v_or_b32_sdwa v83, v83, v85 dst_sel:DWORD dst_unused:UNUSED_PAD src0_sel:BYTE_0 src1_sel:DWORD
	v_and_b32_e32 v84, 0xff0000, v84
	v_or_b32_e32 v83, v83, v84
	v_lshlrev_b32_e32 v84, 16, v89
	v_mul_f32_e32 v79, 0xbfb8aa3b, v79
	v_and_b32_e32 v84, 0xff000000, v84
	v_exp_f32_e32 v79, v79
	v_mul_f32_e32 v80, 0xbfb8aa3b, v80
	v_or_b32_e32 v83, v83, v84
	v_exp_f32_e32 v84, v80
	v_mul_f32_e32 v80, 0xbfb8aa3b, v81
	v_exp_f32_e32 v81, v80
	v_add_f32_e32 v79, 1.0, v79
	v_rcp_f32_e32 v80, v79
	v_add_f32_e32 v79, 1.0, v84
	v_mul_f32_e32 v74, 0xbfb8aa3b, v74
	v_mul_f32_e32 v78, 0xbfb8aa3b, v78
	v_rcp_f32_e32 v84, v79
	v_add_f32_e32 v79, 1.0, v81
	v_exp_f32_e32 v81, v74
	v_mul_f32_e32 v74, 0xbfb8aa3b, v75
	v_exp_f32_e32 v78, v78
	v_exp_f32_e32 v75, v74
	v_mul_f32_e32 v76, 0xbfb8aa3b, v76
	v_exp_f32_e32 v76, v76
	v_mul_f32_e32 v77, 0xbfb8aa3b, v77
	v_lshlrev_b32_e32 v85, 8, v86
	v_exp_f32_e32 v77, v77
	v_and_b32_e32 v85, 0xff0000, v85
	v_or_b32_e32 v82, v82, v85
	v_lshlrev_b32_e32 v85, 16, v88
	v_add_f32_e32 v78, 1.0, v78
	v_rcp_f32_e32 v74, v79
	v_add_f32_e32 v79, 1.0, v81
	v_add_f32_e32 v75, 1.0, v75
	v_and_b32_e32 v85, 0xff000000, v85
	v_rcp_f32_e32 v78, v78
	v_rcp_f32_e32 v79, v79
	v_rcp_f32_e32 v81, v75
	v_add_f32_e32 v75, 1.0, v76
	v_or_b32_e32 v82, v82, v85
	v_rcp_f32_e32 v85, v75
	v_add_f32_e32 v75, 1.0, v77
	v_rcp_f32_e32 v75, v75
	v_pk_fma_f32 v[76:77], v[78:79], s[0:1], v[148:149] op_sel_hi:[1,0,0]
	v_pk_fma_f32 v[78:79], v[80:81], s[0:1], v[148:149] op_sel_hi:[1,0,0]
	v_pk_fma_f32 v[80:81], v[84:85], s[0:1], v[148:149] op_sel_hi:[1,0,0]
	v_lshrrev_b32_e32 v76, 8, v76
	v_and_b32_e32 v78, 0xff00, v78
	v_pk_fma_f32 v[74:75], v[74:75], s[0:1], v[148:149] op_sel_hi:[1,0,0]
	v_lshrrev_b32_e32 v77, 8, v77
	v_and_b32_e32 v79, 0xff00, v79
	v_or_b32_sdwa v76, v76, v78 dst_sel:DWORD dst_unused:UNUSED_PAD src0_sel:BYTE_0 src1_sel:DWORD
	v_lshlrev_b32_e32 v78, 8, v81
	v_or_b32_sdwa v77, v77, v79 dst_sel:DWORD dst_unused:UNUSED_PAD src0_sel:BYTE_0 src1_sel:DWORD
	v_lshlrev_b32_e32 v79, 8, v80
	v_and_b32_e32 v78, 0xff0000, v78
	v_lshlrev_b32_e32 v75, 16, v75
	v_and_b32_e32 v79, 0xff0000, v79
	v_or_b32_e32 v77, v77, v78
	v_lshlrev_b32_e32 v74, 16, v74
	v_and_b32_e32 v75, 0xff000000, v75
	v_or_b32_e32 v76, v76, v79
	v_and_b32_e32 v74, 0xff000000, v74
	v_or_b32_e32 v85, v77, v75
	v_mul_f32_e32 v75, 0xbfb8aa3b, v7
	v_or_b32_e32 v84, v76, v74
	v_exp_f32_e32 v75, v75
	v_mul_f32_e32 v76, 0xbfb8aa3b, v8
	v_exp_f32_e32 v77, v76
	v_mul_f32_e32 v76, 0xbfb8aa3b, v9
	v_exp_f32_e32 v79, v76
	v_add_f32_e32 v75, 1.0, v75
	v_rcp_f32_e32 v76, v75
	v_add_f32_e32 v75, 1.0, v77
	v_rcp_f32_e32 v78, v75
	v_add_f32_e32 v75, 1.0, v79
	v_mul_f32_e32 v77, 0xbfb8aa3b, v2
	v_mul_f32_e32 v79, 0xbfb8aa3b, v3
	v_exp_f32_e32 v77, v77
	v_exp_f32_e32 v79, v79
	v_mul_f32_e32 v74, 0xbfb8aa3b, v6
	v_exp_f32_e32 v74, v74
	v_rcp_f32_e32 v80, v75
	v_add_f32_e32 v75, 1.0, v77
	v_add_f32_e32 v77, 1.0, v79
	v_mul_f32_e32 v79, 0xbfb8aa3b, v4
	v_exp_f32_e32 v79, v79
	v_mul_f32_e32 v81, 0xbfb8aa3b, v5
	v_exp_f32_e32 v81, v81
	v_add_f32_e32 v74, 1.0, v74
	v_rcp_f32_e32 v74, v74
	v_rcp_f32_e32 v75, v75
	v_rcp_f32_e32 v77, v77
	v_add_f32_e32 v79, 1.0, v79
	v_rcp_f32_e32 v79, v79
	v_add_f32_e32 v81, 1.0, v81
	v_rcp_f32_e32 v81, v81
	v_pk_fma_f32 v[74:75], v[74:75], s[0:1], v[148:149] op_sel_hi:[1,0,0]
	v_pk_fma_f32 v[76:77], v[76:77], s[0:1], v[148:149] op_sel_hi:[1,0,0]
	v_pk_fma_f32 v[78:79], v[78:79], s[0:1], v[148:149] op_sel_hi:[1,0,0]
	v_lshrrev_b32_e32 v74, 8, v74
	v_and_b32_e32 v76, 0xff00, v76
	v_lshrrev_b32_e32 v75, 8, v75
	v_and_b32_e32 v77, 0xff00, v77
	v_or_b32_sdwa v74, v74, v76 dst_sel:DWORD dst_unused:UNUSED_PAD src0_sel:BYTE_0 src1_sel:DWORD
	v_lshlrev_b32_e32 v76, 8, v79
	v_pk_fma_f32 v[80:81], v[80:81], s[0:1], v[148:149] op_sel_hi:[1,0,0]
	v_or_b32_sdwa v75, v75, v77 dst_sel:DWORD dst_unused:UNUSED_PAD src0_sel:BYTE_0 src1_sel:DWORD
	v_and_b32_e32 v76, 0xff0000, v76
	v_or_b32_e32 v75, v75, v76
	v_lshlrev_b32_e32 v76, 16, v81
	v_mul_f32_e32 v55, 0xbfb8aa3b, v55
	v_and_b32_e32 v76, 0xff000000, v76
	v_exp_f32_e32 v55, v55
	v_mul_f32_e32 v56, 0xbfb8aa3b, v56
	v_or_b32_e32 v75, v75, v76
	v_exp_f32_e32 v76, v56
	v_mul_f32_e32 v56, 0xbfb8aa3b, v57
	v_exp_f32_e32 v57, v56
	v_add_f32_e32 v55, 1.0, v55
	v_rcp_f32_e32 v56, v55
	v_add_f32_e32 v55, 1.0, v76
	v_mul_f32_e32 v34, 0xbfb8aa3b, v34
	v_mul_f32_e32 v54, 0xbfb8aa3b, v54
	v_rcp_f32_e32 v76, v55
	v_add_f32_e32 v55, 1.0, v57
	v_exp_f32_e32 v57, v34
	v_mul_f32_e32 v34, 0xbfb8aa3b, v35
	v_exp_f32_e32 v54, v54
	v_exp_f32_e32 v35, v34
	v_mul_f32_e32 v36, 0xbfb8aa3b, v36
	v_exp_f32_e32 v36, v36
	v_mul_f32_e32 v37, 0xbfb8aa3b, v37
	v_lshlrev_b32_e32 v77, 8, v78
	v_exp_f32_e32 v37, v37
	v_and_b32_e32 v77, 0xff0000, v77
	v_or_b32_e32 v74, v74, v77
	v_lshlrev_b32_e32 v77, 16, v80
	v_add_f32_e32 v54, 1.0, v54
	v_rcp_f32_e32 v34, v55
	v_add_f32_e32 v55, 1.0, v57
	v_add_f32_e32 v35, 1.0, v35
	v_and_b32_e32 v77, 0xff000000, v77
	v_rcp_f32_e32 v54, v54
	v_rcp_f32_e32 v55, v55
	v_rcp_f32_e32 v57, v35
	v_add_f32_e32 v35, 1.0, v36
	v_or_b32_e32 v74, v74, v77
	v_rcp_f32_e32 v77, v35
	v_add_f32_e32 v35, 1.0, v37
	v_rcp_f32_e32 v35, v35
	v_pk_fma_f32 v[36:37], v[54:55], s[0:1], v[148:149] op_sel_hi:[1,0,0]
	v_pk_fma_f32 v[54:55], v[56:57], s[0:1], v[148:149] op_sel_hi:[1,0,0]
	v_pk_fma_f32 v[56:57], v[76:77], s[0:1], v[148:149] op_sel_hi:[1,0,0]
	v_lshrrev_b32_e32 v37, 8, v37
	v_lshrrev_b32_e32 v36, 8, v36
	v_and_b32_e32 v55, 0xff00, v55
	v_and_b32_e32 v54, 0xff00, v54
	v_pk_fma_f32 v[34:35], v[34:35], s[0:1], v[148:149] op_sel_hi:[1,0,0]
	v_or_b32_sdwa v37, v37, v55 dst_sel:DWORD dst_unused:UNUSED_PAD src0_sel:BYTE_0 src1_sel:DWORD
	v_or_b32_sdwa v36, v36, v54 dst_sel:DWORD dst_unused:UNUSED_PAD src0_sel:BYTE_0 src1_sel:DWORD
	v_lshlrev_b32_e32 v54, 8, v57
	v_lshlrev_b32_e32 v55, 8, v56
	v_and_b32_e32 v54, 0xff0000, v54
	v_and_b32_e32 v55, 0xff0000, v55
	v_lshlrev_b32_e32 v35, 16, v35
	v_lshlrev_b32_e32 v34, 16, v34
	v_or_b32_e32 v37, v37, v54
	v_or_b32_e32 v36, v36, v55
	v_and_b32_e32 v35, 0xff000000, v35
	v_and_b32_e32 v34, 0xff000000, v34
	v_or_b32_e32 v77, v37, v35
	v_or_b32_e32 v76, v36, v34
	global_store_dwordx4 v[150:151], v[156:159], off
	global_store_dwordx4 v[150:151], v[122:125], off offset:1024
	global_store_dwordx4 v[150:151], v[114:117], off offset:2048
	global_store_dwordx4 v[150:151], v[106:109], off offset:3072
	global_store_dwordx4 v[90:91], v[92:95], off offset:1024
	global_store_dwordx4 v[90:91], v[82:85], off offset:2048
	global_store_dwordx4 v[90:91], v[74:77], off offset:3072

.LBB0_116:
	s_and_saveexec_b64 s[0:1], s[22:23]
	s_cbranch_execz .LBB0_118
	s_mov_b32 s98, 16
	v_or_b32_e32 v36, 16, v146
	v_ashrrev_i32_e32 v147, 31, v146
	v_ashrrev_i32_e32 v37, 31, v36
	v_lshlrev_b64 v[34:35], 6, v[146:147]
	v_lshlrev_b64 v[36:37], 6, v[36:37]
	v_lshl_add_u64 v[34:35], v[140:141], 0, v[34:35]
	v_lshl_add_u64 v[36:37], v[140:141], 0, v[36:37]
	global_store_dwordx4 v[34:35], v[70:73], off
	global_store_dwordx4 v[34:35], v[66:69], off offset:16
	global_store_dwordx4 v[36:37], v[62:65], off
	global_store_dwordx4 v[36:37], v[58:61], off offset:16
	v_or_b32_e32 v36, 32, v146
	v_ashrrev_i32_e32 v37, 31, v36
	v_lshlrev_b64 v[36:37], 6, v[36:37]
	v_lshl_add_u64 v[36:37], v[140:141], 0, v[36:37]
	global_store_dwordx4 v[36:37], v[50:53], off
	global_store_dwordx4 v[36:37], v[46:49], off offset:16
	v_or_b32_e32 v36, 48, v146
	v_ashrrev_i32_e32 v37, 31, v36
	v_lshlrev_b64 v[36:37], 6, v[36:37]
	v_lshl_add_u64 v[36:37], v[140:141], 0, v[36:37]
	s_movk_i32 s18, 0x2000
	global_store_dwordx4 v[36:37], v[42:45], off
	global_store_dwordx4 v[36:37], v[38:41], off offset:16
	s_mov_b64 s[30:31], 0x2000
	v_lshl_add_u64 v[36:37], v[34:35], 0, s[30:31]
	v_add_co_u32_e32 v38, vcc, s18, v34
	s_mov_b64 s[30:31], 0x2400
	s_nop 0
	v_addc_co_u32_e32 v39, vcc, 0, v35, vcc
	global_store_dwordx4 v[38:39], v[30:33], off
	global_store_dwordx4 v[36:37], v[26:29], off offset:16
	s_nop 1
	v_lshl_add_u64 v[26:27], v[34:35], 0, s[30:31]
	s_mov_b64 s[30:31], 0x2800
	global_store_dwordx4 v[38:39], v[22:25], off offset:1024
	global_store_dwordx4 v[26:27], v[18:21], off offset:16
	s_nop 1
	v_lshl_add_u64 v[18:19], v[34:35], 0, s[30:31]
	s_mov_b64 s[30:31], 0x2c00
	global_store_dwordx4 v[38:39], v[14:17], off offset:2048
	global_store_dwordx4 v[18:19], v[10:13], off offset:16
	s_nop 1
	v_lshl_add_u64 v[10:11], v[34:35], 0, s[30:31]
	global_store_dwordx4 v[38:39], v[6:9], off offset:3072
	global_store_dwordx4 v[10:11], v[2:5], off offset:16
